# plus norm2 loads batched, ret_out Q/RG/gn prefetch, hazard pads
# speedup vs baseline: 1.0073x; 1.0073x over previous
.LBB0_680:
	s_and_b32 s4, s22, 1
	s_lshl_b32 s5, s22, 6
	s_and_b32 s6, s5, 0xffffff80
	s_cmp_lt_i32 s6, 0x10000
	s_movk_i32 s7, 0xf80
	s_cselect_b32 s7, s7, 0x1f80
	s_movk_i32 s8, 0x2000
	s_cselect_b32 s8, 0x1000, s8
	s_and_b32 s7, s7, s5
	v_lshrrev_b32_e32 v0, 3, v195
	v_bfe_u32 v1, v195, 2, 1
	v_and_b32_e32 v2, 3, v195
	v_lshlrev_b32_e32 v3, 6, v1
	v_lshl_or_b32 v3, v2, 4, v3
	v_mul_u32_u24_e32 v4, 0x28000, v0
	v_add_u32_e32 v146, v4, v3
	v_lshrrev_b32_e32 v4, 1, v3
	v_mul_u32_u24_e32 v4, 0x88, v4
	v_lshl_add_u32 v147, v0, 1, v4
	v_and_b32_e32 v4, 35, v0
	v_bfe_u32 v5, v0, 2, 1
	v_lshl_or_b32 v4, v5, 4, v4
	v_bfe_u32 v5, v0, 3, 2
	v_lshl_or_b32 v4, v5, 2, v4
	v_mul_u32_u24_e32 v4, 0x310, v4
	v_add_u32_e32 v206, v4, v3
	s_lshl_b32 s9, s6, 1
	s_mul_i32 s10, s4, 0xa00000
	s_add_u32 s9, s9, s10
	v_readlane_b32 s10, v254, 9
	v_readlane_b32 s11, v254, 10
	s_add_u32 s10, s10, s9
	s_addc_u32 s11, s11, 0
	v_readlane_b32 s12, v254, 11
	v_readlane_b32 s13, v254, 12
	s_add_u32 s12, s12, s9
	s_addc_u32 s13, s13, 0
	s_nop 1
	global_load_dwordx4 v[156:159], v146, s[10:11]
	global_load_dwordx4 v[160:163], v146, s[10:11] offset:128
	global_load_dwordx4 v[180:183], v146, s[12:13]
	global_load_dwordx4 v[184:187], v146, s[12:13] offset:128
	s_cmp_lg_u32 s7, 0
	s_cbranch_scc0 .Lswa_lo_zero
	global_load_dwordx4 v[148:151], v146, s[10:11] offset:-256
	global_load_dwordx4 v[152:155], v146, s[10:11] offset:-128
	global_load_dwordx4 v[172:175], v146, s[12:13] offset:-256
	global_load_dwordx4 v[176:179], v146, s[12:13] offset:-128
	s_branch .Lswa_lo_done

.Lro_compute:
	s_or_b32 s0, s14, s22
	s_lshl_b64 s[2:3], s[0:1], 2
	s_add_u32 s2, s48, s2
	s_addc_u32 s3, s49, s3
	s_waitcnt lgkmcnt(0)
	s_barrier
	global_load_dword v2, v193, s[2:3]
	global_load_dword v3, v193, s[2:3] offset:16
	s_mov_b32 s0, 0xbfb8aa3b
	s_mov_b32 s2, 0x42ce8ed0
	s_mov_b32 s3, 0x33800000
	v_add_u32_e32 v34, vcc_lo, v38
	v_ashrrev_i32_e32 v35, 31, v34
	v_lshlrev_b64 v[36:37], 9, v[34:35]
	v_lshlrev_b32_e32 v192, 1, v32
	v_lshlrev_b64 v[34:35], 11, v[34:35]
	v_readlane_b32 s98, v254, 15
	v_readlane_b32 s99, v254, 16
	v_readlane_b32 s100, v254, 19
	v_readlane_b32 s101, v254, 20
	v_or_b32_e32 v172, v109, v32
	v_mov_b32_e32 v173, 0
	v_lshl_add_u64 v[174:175], s[98:99], 0, v[36:37]
	v_lshl_add_u64 v[174:175], v[0:1], 1, v[174:175]
	v_lshl_add_u64 v[174:175], v[174:175], 0, v[192:193]
	global_load_dwordx4 v[176:179], v[174:175], off
	global_load_dwordx4 v[180:183], v[174:175], off offset:64
	v_lshl_add_u64 v[174:175], s[100:101], 0, v[36:37]
	v_lshl_add_u64 v[174:175], v[172:173], 1, v[174:175]
	global_load_dwordx4 v[184:187], v[174:175], off
	global_load_dwordx4 v[188:191], v[174:175], off offset:64
	v_lshl_add_u64 v[174:175], v[172:173], 2, s[92:93]
	global_load_dwordx4 v[208:211], v[174:175], off
	global_load_dwordx4 v[212:215], v[174:175], off offset:16
	global_load_dwordx4 v[216:219], v[174:175], off offset:128
	global_load_dwordx4 v[244:247], v[174:175], off offset:144
	s_waitcnt vmcnt(9)
	v_mul_f32_e32 v4, 0xbfb8aa3b, v2
	v_fma_f32 v5, v2, s0, -v4
	v_rndne_f32_e32 v6, v4
	v_fmac_f32_e32 v5, 0xb2a5705f, v2
	v_sub_f32_e32 v4, v4, v6
	v_add_f32_e32 v4, v4, v5
	v_cvt_i32_f32_e32 v6, v6
	v_exp_f32_e32 v4, v4
	s_waitcnt vmcnt(8)
	v_mul_f32_e32 v5, 0xbfb8aa3b, v3
	v_rndne_f32_e32 v7, v5
	v_cmp_nlt_f32_e64 s[68:69], s2, v2
	v_ldexp_f32 v4, v4, v6
	v_fma_f32 v6, v3, s0, -v5
	v_fmac_f32_e32 v6, 0xb2a5705f, v3
	v_sub_f32_e32 v5, v5, v7
	v_add_f32_e32 v5, v5, v6
	v_cvt_i32_f32_e32 v7, v7
	v_exp_f32_e32 v5, v5
	v_cndmask_b32_e64 v4, 0, v4, s[68:69]
	v_cmp_nlt_f32_e64 s[68:69], s2, v3
	s_mov_b32 s0, 0xc2b17218
	v_ldexp_f32 v5, v5, v7
	v_cndmask_b32_e64 v5, 0, v5, s[68:69]
	v_cmp_ngt_f32_e64 s[68:69], s0, v2
	s_mov_b32 s2, 0x3f317218
	s_nop 0
	v_cndmask_b32_e64 v18, v224, v4, s[68:69]
	v_cmp_ngt_f32_e64 s[68:69], s0, v3
	v_add_f32_e32 v4, 1.0, v18
	v_cvt_f64_f32_e32 v[2:3], v4
	v_cndmask_b32_e64 v19, v224, v5, s[68:69]
	v_frexp_mant_f32_e32 v5, v4
	s_mov_b32 s0, 0x3f2aaaab
	v_frexp_exp_i32_f64_e32 v2, v[2:3]
	v_cmp_gt_f32_e64 s[68:69], s0, v5
	v_add_f32_e32 v20, 1.0, v19
	v_frexp_mant_f32_e32 v6, v20
	v_subbrev_co_u32_e64 v5, s[68:69], 0, v2, s[68:69]
	v_cvt_f64_f32_e32 v[2:3], v20
	v_frexp_exp_i32_f64_e32 v2, v[2:3]
	v_cmp_gt_f32_e64 s[68:69], s0, v6
	v_sub_u32_e32 v6, 0, v5
	s_mov_b32 s0, 0x7f800000
	v_subbrev_co_u32_e64 v21, s[68:69], 0, v2, s[68:69]
	v_add_f32_e32 v2, -1.0, v4
	v_sub_f32_e32 v3, v2, v4
	v_sub_f32_e32 v2, v18, v2
	v_add_f32_e32 v3, 1.0, v3
	v_add_f32_e32 v3, v2, v3
	v_ldexp_f32 v4, v4, v6
	v_ldexp_f32 v3, v3, v6
	v_add_f32_e32 v6, -1.0, v4
	v_add_f32_e32 v7, 1.0, v4
	v_cvt_f32_i32_e32 v2, v5
	v_add_f32_e32 v5, 1.0, v6
	v_add_f32_e32 v8, -1.0, v7
	v_sub_f32_e32 v5, v4, v5
	v_sub_f32_e32 v4, v4, v8
	v_add_f32_e32 v8, v3, v5
	v_add_f32_e32 v3, v3, v4
	v_add_f32_e32 v10, v7, v3
	v_rcp_f32_e32 v11, v10
	v_add_f32_e32 v5, v6, v8
	v_sub_f32_e32 v6, v6, v5
	v_sub_f32_e32 v4, v7, v10
	v_mul_f32_e32 v13, v5, v11
	v_add_f32_e32 v12, v8, v6
	v_mul_f32_e32 v6, v10, v13
	v_add_f32_e32 v3, v3, v4
	v_fma_f32 v8, v13, v10, -v6
	v_fmac_f32_e32 v8, v13, v3
	v_add_f32_e32 v4, v6, v8
	v_sub_f32_e32 v7, v5, v4
	v_mov_b32_e32 v9, v4
	v_pk_add_f32 v[4:5], v[4:5], v[6:7] neg_lo:[0,1] neg_hi:[0,1]
	v_cmp_neq_f32_e64 s[68:69], s0, v18
	v_pk_add_f32 v[4:5], v[4:5], v[8:9] neg_lo:[0,1] neg_hi:[0,1]
	s_nop 0
	v_add_f32_e32 v5, v12, v5
	v_add_f32_e32 v4, v4, v5
	v_add_f32_e32 v5, v7, v4
	v_mul_f32_e32 v9, v11, v5
	v_mul_f32_e32 v6, v10, v9
	v_sub_f32_e32 v7, v7, v5
	v_add_f32_e32 v14, v13, v9
	v_fma_f32 v8, v9, v10, -v6
	v_add_f32_e32 v12, v4, v7
	v_sub_f32_e32 v4, v14, v13
	v_fmac_f32_e32 v8, v9, v3
	v_sub_f32_e32 v3, v9, v4
	v_add_f32_e32 v4, v6, v8
	v_sub_f32_e32 v7, v5, v4
	v_mov_b32_e32 v9, v4
	v_pk_add_f32 v[4:5], v[4:5], v[6:7] neg_lo:[0,1] neg_hi:[0,1]
	s_nop 0
	v_pk_add_f32 v[4:5], v[4:5], v[8:9] neg_lo:[0,1] neg_hi:[0,1]
	s_nop 0
	v_add_f32_e32 v5, v12, v5
	v_add_f32_e32 v4, v4, v5
	v_add_f32_e32 v4, v7, v4
	v_mul_f32_e32 v4, v11, v4
	v_add_f32_e32 v3, v3, v4
	v_add_f32_e32 v4, v14, v3
	v_mul_f32_e32 v6, v4, v4
	v_sub_f32_e32 v7, v4, v14
	v_fmamk_f32 v8, v6, 0x3e9b6dac, v221
	v_sub_f32_e32 v7, v3, v7
	v_mul_f32_e32 v3, v4, v6
	v_fmaak_f32 v201, v6, v8, 0x3f2aaada
	v_ldexp_f32 v9, v7, 1
	v_pk_mul_f32 v[6:7], v[2:3], v[200:201]
	v_ldexp_f32 v5, v4, 1
	v_fma_f32 v4, v2, s2, -v6
	v_fmac_f32_e32 v4, 0xb102e308, v2
	v_pk_add_f32 v[2:3], v[6:7], v[4:5]
	v_mov_b32_e32 v8, v6
	v_sub_f32_e32 v12, v3, v5
	v_pk_add_f32 v[10:11], v[2:3], v[6:7] neg_lo:[0,1] neg_hi:[0,1]
	v_sub_f32_e32 v7, v7, v12
	v_add_f32_e32 v9, v9, v7
	v_pk_add_f32 v[14:15], v[2:3], v[8:9]
	v_mov_b32_e32 v5, v2
	v_mov_b32_e32 v11, v15
	v_pk_add_f32 v[16:17], v[4:5], v[10:11] neg_lo:[0,1] neg_hi:[0,1]
	v_pk_add_f32 v[4:5], v[4:5], v[10:11]
	v_mov_b32_e32 v6, v3
	v_mov_b32_e32 v13, v2
	v_pk_add_f32 v[2:3], v[4:5], v[2:3] op_sel:[1,0] op_sel_hi:[0,1] neg_lo:[0,1] neg_hi:[0,1]
	v_mov_b32_e32 v12, v9
	v_mov_b32_e32 v8, v15
	v_mov_b32_e32 v9, v5
	v_mov_b32_e32 v7, v2
	v_pk_add_f32 v[10:11], v[14:15], v[2:3] op_sel_hi:[1,0] neg_lo:[0,1] neg_hi:[0,1]
	v_pk_add_f32 v[2:3], v[8:9], v[6:7] neg_lo:[0,1] neg_hi:[0,1]
	v_mov_b32_e32 v10, v16
	v_pk_add_f32 v[2:3], v[12:13], v[2:3] neg_lo:[0,1] neg_hi:[0,1]
	v_mov_b32_e32 v17, v5
	v_pk_add_f32 v[6:7], v[10:11], v[2:3]
	s_nop 0
	v_pk_add_f32 v[8:9], v[6:7], v[6:7] op_sel:[0,1] op_sel_hi:[1,0]
	s_nop 0
	v_pk_add_f32 v[4:5], v[4:5], v[8:9] op_sel:[1,0] op_sel_hi:[0,1]
	v_mov_b32_e32 v7, v4
	v_mov_b32_e32 v3, v8
	v_pk_add_f32 v[8:9], v[6:7], v[16:17] neg_lo:[0,1] neg_hi:[0,1]
	s_nop 0
	v_sub_f32_e32 v5, v6, v8
	v_pk_add_f32 v[2:3], v[2:3], v[8:9] neg_lo:[0,1] neg_hi:[0,1]
	v_sub_f32_e32 v5, v16, v5
	v_add_f32_e32 v2, v2, v5
	v_add_f32_e32 v2, v2, v3
	v_add_f32_e32 v2, v4, v2
	v_cndmask_b32_e64 v2, v224, v2, s[68:69]
	v_cmp_lt_f32_e64 s[68:69], |v18|, s3
	s_nop 1
	v_cndmask_b32_e64 v18, v2, v18, s[68:69]
	v_add_f32_e32 v2, -1.0, v20
	v_sub_f32_e32 v3, v2, v20
	v_sub_f32_e32 v2, v19, v2
	v_add_f32_e32 v3, 1.0, v3
	v_add_f32_e32 v2, v2, v3
	v_sub_u32_e32 v3, 0, v21
	v_ldexp_f32 v4, v20, v3
	v_add_f32_e32 v5, -1.0, v4
	v_ldexp_f32 v2, v2, v3
	v_add_f32_e32 v3, 1.0, v5
	v_sub_f32_e32 v3, v4, v3
	v_add_f32_e32 v6, v2, v3
	v_add_f32_e32 v3, 1.0, v4
	v_add_f32_e32 v7, -1.0, v3
	v_sub_f32_e32 v4, v4, v7
	v_add_f32_e32 v2, v2, v4
	v_add_f32_e32 v10, v3, v2
	v_rcp_f32_e32 v12, v10
	v_sub_f32_e32 v3, v3, v10
	v_add_f32_e32 v11, v2, v3
	v_add_f32_e32 v3, v5, v6
	v_mul_f32_e32 v14, v3, v12
	v_sub_f32_e32 v2, v5, v3
	v_mul_f32_e32 v4, v10, v14
	v_add_f32_e32 v13, v6, v2
	v_fma_f32 v6, v14, v10, -v4
	v_fmac_f32_e32 v6, v14, v11
	v_add_f32_e32 v2, v4, v6
	v_sub_f32_e32 v5, v3, v2
	v_pk_add_f32 v[8:9], v[2:3], v[4:5] neg_lo:[0,1] neg_hi:[0,1]
	v_mov_b32_e32 v7, v2
	v_pk_add_f32 v[2:3], v[8:9], v[6:7] neg_lo:[0,1] neg_hi:[0,1]
	v_cmp_neq_f32_e64 s[68:69], s0, v19
	v_add_f32_e32 v3, v13, v3
	v_add_f32_e32 v2, v2, v3
	v_add_f32_e32 v3, v5, v2
	v_mul_f32_e32 v13, v12, v3
	v_mul_f32_e32 v4, v10, v13
	v_fma_f32 v6, v13, v10, -v4
	v_fmac_f32_e32 v6, v13, v11
	v_sub_f32_e32 v5, v5, v3
	v_add_f32_e32 v10, v2, v5
	v_add_f32_e32 v2, v4, v6
	v_sub_f32_e32 v5, v3, v2
	v_pk_add_f32 v[8:9], v[2:3], v[4:5] neg_lo:[0,1] neg_hi:[0,1]
	v_mov_b32_e32 v7, v2
	v_pk_add_f32 v[2:3], v[8:9], v[6:7] neg_lo:[0,1] neg_hi:[0,1]
	v_mul_f32_e32 v110, 0xbfb8aa3b, v18
	v_add_f32_e32 v3, v10, v3
	v_add_f32_e32 v2, v2, v3
	v_add_f32_e32 v3, v14, v13
	v_add_f32_e32 v2, v5, v2
	v_sub_f32_e32 v4, v3, v14
	v_mul_f32_e32 v2, v12, v2
	v_sub_f32_e32 v4, v13, v4
	v_add_f32_e32 v4, v4, v2
	v_add_f32_e32 v6, v3, v4
	v_mul_f32_e32 v7, v6, v6
	v_fmamk_f32 v2, v7, 0x3e9b6dac, v221
	v_fmaak_f32 v201, v7, v2, 0x3f2aaada
	v_cvt_f32_i32_e32 v2, v21
	v_sub_f32_e32 v3, v6, v3
	v_sub_f32_e32 v3, v4, v3
	v_ldexp_f32 v8, v3, 1
	v_mul_f32_e32 v3, v6, v7
	v_ldexp_f32 v5, v6, 1
	v_pk_mul_f32 v[6:7], v[2:3], v[200:201]
	v_mul_f32_e32 v23, v110, v51
	v_fma_f32 v4, v2, s2, -v6
	v_fmac_f32_e32 v4, 0xb102e308, v2
	v_pk_add_f32 v[2:3], v[6:7], v[4:5]
	v_mul_f32_e32 v27, v110, v67
	v_sub_f32_e32 v5, v3, v5
	v_sub_f32_e32 v5, v7, v5
	v_add_f32_e32 v9, v8, v5
	v_mov_b32_e32 v8, v6
	v_pk_add_f32 v[6:7], v[2:3], v[6:7] neg_lo:[0,1] neg_hi:[0,1]
	v_pk_add_f32 v[10:11], v[2:3], v[8:9]
	v_mov_b32_e32 v5, v2
	v_mov_b32_e32 v7, v11
	v_pk_add_f32 v[12:13], v[4:5], v[6:7] neg_lo:[0,1] neg_hi:[0,1]
	v_pk_add_f32 v[4:5], v[4:5], v[6:7]
	v_mov_b32_e32 v16, v3
	v_pk_add_f32 v[6:7], v[4:5], v[2:3] op_sel:[1,0] op_sel_hi:[0,1] neg_lo:[0,1] neg_hi:[0,1]
	v_pk_add_f32 v[14:15], v[10:11], v[6:7] op_sel_hi:[1,0] neg_lo:[0,1] neg_hi:[0,1]
	v_mov_b32_e32 v10, v11
	v_mov_b32_e32 v11, v5
	v_mov_b32_e32 v17, v6
	v_pk_add_f32 v[6:7], v[10:11], v[16:17] neg_lo:[0,1] neg_hi:[0,1]
	v_mov_b32_e32 v8, v9
	v_mov_b32_e32 v9, v2
	v_pk_add_f32 v[2:3], v[8:9], v[6:7] neg_lo:[0,1] neg_hi:[0,1]
	v_mov_b32_e32 v14, v12
	v_pk_add_f32 v[6:7], v[14:15], v[2:3]
	v_mov_b32_e32 v13, v5
	v_pk_add_f32 v[8:9], v[6:7], v[6:7] op_sel:[0,1] op_sel_hi:[1,0]
	v_mul_f32_e32 v122, v110, v99
	v_pk_add_f32 v[4:5], v[4:5], v[8:9] op_sel:[1,0] op_sel_hi:[0,1]
	v_mov_b32_e32 v7, v4
	v_pk_add_f32 v[10:11], v[6:7], v[12:13] neg_lo:[0,1] neg_hi:[0,1]
	v_mov_b32_e32 v3, v8
	v_sub_f32_e32 v5, v6, v10
	v_pk_add_f32 v[2:3], v[2:3], v[10:11] neg_lo:[0,1] neg_hi:[0,1]
	v_sub_f32_e32 v5, v12, v5
	v_add_f32_e32 v2, v2, v5
	v_add_f32_e32 v2, v2, v3
	v_add_f32_e32 v2, v4, v2
	v_cndmask_b32_e64 v2, v224, v2, s[68:69]
	v_cmp_lt_f32_e64 s[68:69], |v19|, s3
	v_readlane_b32 s2, v254, 15
	v_readlane_b32 s3, v254, 16
	v_cndmask_b32_e64 v16, v2, v19, s[68:69]
	v_mul_f32_e32 v2, v110, v42
	v_cmp_gt_f32_e64 s[68:69], s96, v2
	v_lshl_add_u64 v[2:3], s[2:3], 0, v[36:37]
	v_lshl_add_u64 v[0:1], v[0:1], 1, v[2:3]
	v_lshl_add_u64 v[0:1], v[0:1], 0, v[192:193]
	s_waitcnt vmcnt(0)
	v_mov_b32_e32 v4, v176
	v_mov_b32_e32 v5, v177
	v_mov_b32_e32 v6, v178
	v_mov_b32_e32 v7, v179
	s_nop 0
	v_mov_b32_e32 v0, v180
	v_mov_b32_e32 v1, v181
	v_mov_b32_e32 v2, v182
	v_mov_b32_e32 v3, v183
	ds_read2_b64 v[8:11], v39 offset1:1
	ds_read2_b64 v[12:15], v39 offset0:8 offset1:9
	s_waitcnt lgkmcnt(1)
	v_mfma_f32_16x16x32_bf16 v[8:11], v[8:11], v[4:7], 0
	v_mul_f32_e32 v113, 0xbfb8aa3b, v16
	v_readlane_b32 s2, v254, 49
	v_readlane_b32 s3, v254, 50
	s_waitcnt lgkmcnt(0)
	v_mfma_f32_16x16x32_bf16 v[8:11], v[12:15], v[0:3], v[8:11]
	v_mul_f32_e32 v12, v113, v44
	v_mul_f32_e32 v13, v110, v45
	v_cndmask_b32_e64 v12, v13, v12, s[24:25]
	v_exp_f32_e32 v20, v12
	v_mul_f32_e32 v12, v110, v47
	v_mul_f32_e32 v13, v113, v46
	v_cndmask_b32_e64 v12, v12, v13, s[2:3]
	v_exp_f32_e32 v21, v12
	ds_read2_b64 v[12:15], v39 offset0:68 offset1:69
	v_mul_f32_e32 v16, v113, v43
	v_readlane_b32 s2, v254, 51
	v_cndmask_b32_e64 v111, 0, v225, s[68:69]
	v_cndmask_b32_e64 v112, 0, v226, s[68:69]
	v_cmp_gt_f32_e64 s[68:69], s96, v16
	v_mul_f32_e32 v16, v110, v49
	v_mul_f32_e32 v17, v113, v48
	v_readlane_b32 s3, v254, 52
	v_mul_f32_e32 v24, v113, v50
	v_pk_mul_f32 v[28:29], v[8:9], v[20:21]
	v_cndmask_b32_e64 v16, v16, v17, s[2:3]
	v_exp_f32_e32 v22, v16
	ds_read2_b64 v[16:19], v39 offset0:76 offset1:77
	v_readlane_b32 s2, v254, 53
	v_readlane_b32 s3, v254, 54
	s_waitcnt lgkmcnt(1)
	v_mfma_f32_16x16x32_bf16 v[12:15], v[12:15], v[4:7], 0
	v_mul_f32_e32 v20, v113, v58
	v_cndmask_b32_e64 v23, v23, v24, s[2:3]
	v_exp_f32_e32 v23, v23
	v_readlane_b32 s2, v254, 55
	v_readlane_b32 s3, v254, 56
	v_mul_f32_e32 v21, v113, v64
	v_pk_mul_f32 v[116:117], v[10:11], v[22:23]
	s_waitcnt lgkmcnt(0)
	v_mfma_f32_16x16x32_bf16 v[8:11], v[16:19], v[0:3], v[12:15]
	v_mul_f32_e32 v30, v113, v66
	v_mul_f32_e32 v144, v110, v101
	v_mul_f32_e32 v145, v113, v100
	v_mul_f32_e32 v12, v110, v53
	v_mul_f32_e32 v13, v113, v52
	v_cndmask_b32_e64 v12, v12, v13, s[2:3]
	v_readlane_b32 s2, v254, 57
	v_exp_f32_e32 v16, v12
	v_mul_f32_e32 v12, v110, v55
	v_mul_f32_e32 v13, v113, v54
	v_readlane_b32 s3, v254, 58
	v_cndmask_b32_e64 v114, 0, v225, s[68:69]
	v_cndmask_b32_e64 v115, 0, v226, s[68:69]
	v_cndmask_b32_e64 v12, v12, v13, s[2:3]
	v_exp_f32_e32 v17, v12
	v_add_u32_e32 v12, 0x1100, v39
	ds_read2_b64 v[12:15], v12 offset1:1
	v_readlane_b32 s2, v254, 59
	v_pk_mul_f32 v[118:119], v[8:9], v[16:17]
	v_add_u32_e32 v9, 0x1140, v39
	ds_read2_b64 v[16:19], v9 offset1:1
	v_mul_f32_e32 v8, v110, v57
	v_mul_f32_e32 v9, v113, v56
	v_readlane_b32 s3, v254, 60
	s_waitcnt lgkmcnt(1)
	v_mfma_f32_16x16x32_bf16 v[12:15], v[12:15], v[4:7], 0
	v_cndmask_b32_e64 v8, v8, v9, s[2:3]
	v_readlane_b32 s2, v254, 61
	v_mul_f32_e32 v9, v110, v59
	v_readlane_b32 s3, v254, 62
	s_waitcnt lgkmcnt(0)
	v_mfma_f32_16x16x32_bf16 v[12:15], v[16:19], v[0:3], v[12:15]
	v_mul_f32_e32 v16, v110, v61
	v_cndmask_b32_e64 v9, v9, v20, s[2:3]
	v_readlane_b32 s2, v254, 63
	v_mul_f32_e32 v17, v113, v60
	v_readlane_b32 s3, v255, 0
	v_mul_f32_e32 v20, v110, v65
	v_exp_f32_e32 v8, v8
	v_cndmask_b32_e64 v16, v16, v17, s[2:3]
	v_readlane_b32 s2, v255, 1
	v_exp_f32_e32 v24, v16
	v_mul_f32_e32 v16, v110, v63
	v_mul_f32_e32 v17, v113, v62
	v_readlane_b32 s3, v255, 2
	v_exp_f32_e32 v9, v9
	v_fmac_f32_e32 v111, v110, v42
	v_cndmask_b32_e64 v16, v16, v17, s[2:3]
	v_exp_f32_e32 v25, v16
	v_add_u32_e32 v16, 0x1320, v39
	ds_read2_b64 v[16:19], v16 offset1:1
	v_readlane_b32 s2, v255, 3
	v_readlane_b32 s3, v255, 4
	v_pk_mul_f32 v[124:125], v[12:13], v[24:25]
	v_mul_f32_e32 v12, v110, v69
	v_cndmask_b32_e64 v20, v20, v21, s[2:3]
	v_exp_f32_e32 v26, v20
	v_add_u32_e32 v20, 0x1360, v39
	ds_read2_b64 v[20:23], v20 offset1:1
	v_readlane_b32 s2, v255, 5
	s_waitcnt lgkmcnt(1)
	v_mfma_f32_16x16x32_bf16 v[16:19], v[16:19], v[4:7], 0
	v_readlane_b32 s3, v255, 6
	v_mul_f32_e32 v13, v113, v68
	v_cndmask_b32_e64 v12, v12, v13, s[26:27]
	v_cndmask_b32_e64 v27, v27, v30, s[2:3]
	v_exp_f32_e32 v27, v27
	v_pk_mul_f32 v[120:121], v[10:11], v[8:9]
	s_waitcnt lgkmcnt(0)
	v_mfma_f32_16x16x32_bf16 v[8:11], v[20:23], v[0:3], v[16:19]
	v_mul_f32_e32 v13, v113, v70
	v_pk_mul_f32 v[126:127], v[14:15], v[26:27]
	v_mul_f32_e32 v20, v113, v74
	v_exp_f32_e32 v16, v12
	v_mul_f32_e32 v12, v110, v71
	v_cndmask_b32_e64 v12, v12, v13, s[28:29]
	v_exp_f32_e32 v17, v12
	v_add_u32_e32 v12, 0x2200, v39
	ds_read2_b64 v[12:15], v12 offset1:1
	v_mul_f32_e32 v21, v113, v80
	v_pk_mul_f32 v[128:129], v[8:9], v[16:17]
	v_add_u32_e32 v9, 0x2240, v39
	ds_read2_b64 v[16:19], v9 offset1:1
	s_waitcnt lgkmcnt(1)
	v_mfma_f32_16x16x32_bf16 v[12:15], v[12:15], v[4:7], 0
	v_mul_f32_e32 v8, v110, v73
	v_mul_f32_e32 v9, v113, v72
	s_waitcnt lgkmcnt(0)
	v_mfma_f32_16x16x32_bf16 v[12:15], v[16:19], v[0:3], v[12:15]
	v_mul_f32_e32 v16, v110, v77
	v_mul_f32_e32 v17, v113, v76
	v_cndmask_b32_e64 v16, v16, v17, s[36:37]
	v_exp_f32_e32 v24, v16
	v_mul_f32_e32 v16, v110, v79
	v_mul_f32_e32 v17, v113, v78
	v_cndmask_b32_e64 v16, v16, v17, s[38:39]
	v_exp_f32_e32 v25, v16
	v_add_u32_e32 v16, 0x2420, v39
	v_cndmask_b32_e64 v8, v8, v9, s[30:31]
	v_mul_f32_e32 v9, v110, v75
	ds_read2_b64 v[16:19], v16 offset1:1
	v_cndmask_b32_e64 v9, v9, v20, s[34:35]
	v_mul_f32_e32 v20, v110, v81
	v_cndmask_b32_e64 v20, v20, v21, s[40:41]
	v_exp_f32_e32 v26, v20
	v_add_u32_e32 v20, 0x2460, v39
	ds_read2_b64 v[20:23], v20 offset1:1
	v_exp_f32_e32 v8, v8
	v_exp_f32_e32 v9, v9
	s_waitcnt lgkmcnt(1)
	v_mfma_f32_16x16x32_bf16 v[16:19], v[16:19], v[4:7], 0
	v_mul_f32_e32 v27, v110, v83
	v_mul_f32_e32 v30, v113, v82
	v_cndmask_b32_e64 v27, v27, v30, s[42:43]
	v_pk_mul_f32 v[132:133], v[12:13], v[24:25]
	v_mul_f32_e32 v12, v110, v85
	v_mul_f32_e32 v13, v113, v84
	v_exp_f32_e32 v27, v27
	v_cndmask_b32_e64 v12, v12, v13, s[44:45]
	v_pk_mul_f32 v[130:131], v[10:11], v[8:9]
	s_waitcnt lgkmcnt(0)
	v_mfma_f32_16x16x32_bf16 v[8:11], v[20:23], v[0:3], v[16:19]
	v_mul_f32_e32 v13, v113, v86
	v_pk_mul_f32 v[134:135], v[14:15], v[26:27]
	v_mul_f32_e32 v20, v113, v90
	v_exp_f32_e32 v16, v12
	v_mul_f32_e32 v12, v110, v87
	v_cndmask_b32_e64 v12, v12, v13, s[46:47]
	v_exp_f32_e32 v17, v12
	v_add_u32_e32 v12, 0x3300, v39
	ds_read2_b64 v[12:15], v12 offset1:1
	v_mul_f32_e32 v21, v113, v94
	v_pk_mul_f32 v[136:137], v[8:9], v[16:17]
	v_add_u32_e32 v9, 0x3340, v39
	ds_read2_b64 v[16:19], v9 offset1:1
	s_waitcnt lgkmcnt(1)
	v_mfma_f32_16x16x32_bf16 v[12:15], v[12:15], v[4:7], 0
	v_mul_f32_e32 v8, v110, v89
	v_mul_f32_e32 v9, v113, v88
	s_waitcnt lgkmcnt(0)
	v_mfma_f32_16x16x32_bf16 v[12:15], v[16:19], v[0:3], v[12:15]
	v_mul_f32_e32 v16, v110, v93
	v_mul_f32_e32 v17, v113, v92
	v_cndmask_b32_e64 v16, v16, v17, s[76:77]
	v_exp_f32_e32 v138, v16
	v_add_u32_e32 v16, 0x3520, v39
	v_cndmask_b32_e64 v8, v8, v9, s[70:71]
	v_mul_f32_e32 v9, v110, v91
	ds_read2_b64 v[16:19], v16 offset1:1
	v_cndmask_b32_e64 v9, v9, v20, s[74:75]
	v_mul_f32_e32 v20, v110, v95
	v_cndmask_b32_e64 v20, v20, v21, s[78:79]
	v_exp_f32_e32 v139, v20
	v_add_u32_e32 v20, 0x3560, v39
	ds_read2_b64 v[20:23], v20 offset1:1
	s_waitcnt lgkmcnt(1)
	v_mfma_f32_16x16x32_bf16 v[16:19], v[16:19], v[4:7], 0
	v_mul_f32_e32 v24, v110, v97
	v_mul_f32_e32 v25, v113, v96
	v_cndmask_b32_e64 v30, v24, v25, s[80:81]
	s_waitcnt lgkmcnt(0)
	v_mfma_f32_16x16x32_bf16 v[20:23], v[20:23], v[0:3], v[16:19]
	ds_read_b128 v[24:27], v40 offset:17408
	s_nop 1
	v_cvt_pk_bf16_f32 v19, v120, v121
	v_mul_f32_e32 v120, v113, v98
	v_cndmask_b32_e64 v120, v122, v120, s[82:83]
	v_exp_f32_e32 v140, v30
	v_cvt_pk_bf16_f32 v16, v28, v29
	ds_read_b128 v[28:31], v40 offset:21760
	v_cvt_pk_bf16_f32 v17, v116, v117
	v_cvt_pk_bf16_f32 v18, v118, v119
	ds_read_b128 v[116:119], v40 offset:26112
	v_exp_f32_e32 v141, v120
	ds_read_b128 v[120:123], v40 offset:30464
	v_exp_f32_e32 v8, v8
	v_exp_f32_e32 v9, v9
	v_pk_mul_f32 v[138:139], v[12:13], v[138:139]
	v_pk_mul_f32 v[140:141], v[14:15], v[140:141]
	ds_read_b128 v[12:15], v40 offset:17472
	s_waitcnt lgkmcnt(4)
	v_mfma_f32_16x16x32_bf16 v[24:27], v[24:27], v[16:19], 0
	v_mul_f32_e64 v142, v10, v8
	v_mul_f32_e64 v143, v11, v9
	v_fmac_f32_e32 v114, v113, v43
	s_mov_b32 s0, 0x800000
	s_waitcnt lgkmcnt(3)
	v_mfma_f32_16x16x32_bf16 v[28:31], v[28:31], v[16:19], 0
	v_readlane_b32 s2, v254, 19
	v_or_b32_e32 v192, v109, v32
	v_readlane_b32 s3, v254, 20
	s_waitcnt lgkmcnt(2)
	v_mfma_f32_16x16x32_bf16 v[8:11], v[116:119], v[16:19], 0
	v_cvt_pk_bf16_f32 v116, v124, v125
	v_cvt_pk_bf16_f32 v117, v126, v127
	v_cvt_pk_bf16_f32 v118, v128, v129
	s_waitcnt lgkmcnt(1)
	v_mfma_f32_16x16x32_bf16 v[16:19], v[120:123], v[16:19], 0
	ds_read_b128 v[120:123], v40 offset:21824
	v_cvt_pk_bf16_f32 v119, v130, v131
	v_cndmask_b32_e64 v124, v144, v145, s[88:89]
	v_exp_f32_e32 v128, v124
	s_waitcnt lgkmcnt(1)
	v_mfma_f32_16x16x32_bf16 v[12:15], v[12:15], v[116:119], v[24:27]
	v_mul_f32_e32 v124, v110, v103
	v_mul_f32_e32 v125, v113, v102
	v_cndmask_b32_e64 v124, v124, v125, s[90:91]
	ds_read_b128 v[24:27], v40 offset:26176
	s_waitcnt lgkmcnt(1)
	v_mfma_f32_16x16x32_bf16 v[28:31], v[120:123], v[116:119], v[28:31]
	ds_read_b128 v[120:123], v40 offset:30528
	v_mul_f32_e32 v130, v110, v105
	s_waitcnt lgkmcnt(1)
	v_mfma_f32_16x16x32_bf16 v[8:11], v[24:27], v[116:119], v[8:11]
	ds_read_b128 v[24:27], v40 offset:17536
	v_mul_f32_e32 v131, v113, v104
	v_exp_f32_e32 v129, v124
	s_waitcnt lgkmcnt(1)
	v_mfma_f32_16x16x32_bf16 v[116:119], v[120:123], v[116:119], v[16:19]
	v_cvt_pk_bf16_f32 v120, v132, v133
	v_cvt_pk_bf16_f32 v121, v134, v135
	v_cvt_pk_bf16_f32 v122, v136, v137
	ds_read_b128 v[16:19], v40 offset:21888
	v_cvt_pk_bf16_f32 v123, v142, v143
	s_waitcnt lgkmcnt(1)
	s_nop 0
	v_mfma_f32_16x16x32_bf16 v[124:127], v[24:27], v[120:123], v[12:15]
	ds_read_b128 v[24:27], v40 offset:26240
	s_nop 1
	v_cndmask_b32_e64 v12, v130, v131, s[64:65]
	v_exp_f32_e32 v130, v12
	s_waitcnt lgkmcnt(1)
	v_mfma_f32_16x16x32_bf16 v[12:15], v[16:19], v[120:123], v[28:31]
	v_mul_f32_e32 v131, v110, v107
	v_mul_f32_e32 v16, v113, v106
	v_cndmask_b32_e64 v16, v131, v16, s[66:67]
	ds_read_b128 v[28:31], v40 offset:30592
	v_exp_f32_e32 v131, v16
	s_waitcnt lgkmcnt(1)
	v_mfma_f32_16x16x32_bf16 v[16:19], v[24:27], v[120:123], v[8:11]
	v_mul_f32_e64 v26, v20, v128
	v_mul_f32_e64 v27, v21, v129
	v_pk_mul_f32 v[128:129], v[22:23], v[130:131]
	v_cvt_pk_bf16_f32 v24, v138, v139
	ds_read_b128 v[8:11], v40 offset:17600
	s_waitcnt lgkmcnt(1)
	v_mfma_f32_16x16x32_bf16 v[20:23], v[28:31], v[120:123], v[116:119]
	ds_read_b128 v[28:31], v40 offset:21952
	v_cvt_pk_bf16_f32 v25, v140, v141
	s_nop 0
	v_add_u32_e32 v116, 64, v242
	v_cvt_pk_bf16_f32 v26, v26, v27
	v_cvt_pk_bf16_f32 v27, v128, v129
	v_cmp_lt_i32_e64 s[68:69], v237, v116
	v_exp_f32_e32 v110, v111
	s_waitcnt lgkmcnt(0)
	v_mfma_f32_16x16x32_bf16 v[12:15], v[28:31], v[24:27], v[12:15]
	v_cndmask_b32_e64 v144, v220, v237, s[68:69]
	v_cmp_lt_i32_e64 s[68:69], v236, v116
	ds_read_b128 v[28:31], v40 offset:26304
	ds_read_b128 v[116:119], v40 offset:30656
	s_waitcnt lgkmcnt(1)
	v_mfma_f32_16x16x32_bf16 v[16:19], v[28:31], v[24:27], v[16:19]
	ds_read_b128 v[28:31], v41 offset:34816
	ds_read_b128 v[120:123], v41 offset:37120
	ds_read_b128 v[128:131], v41 offset:39424
	v_mfma_f32_16x16x32_bf16 v[8:11], v[8:11], v[24:27], v[124:127]
	ds_read_b128 v[132:135], v41 offset:48640
	ds_read_b128 v[136:139], v41 offset:41728
	ds_read_b128 v[140:143], v41 offset:50944
	s_waitcnt lgkmcnt(6)
	v_mfma_f32_16x16x32_bf16 v[20:23], v[116:119], v[24:27], v[20:23]
	ds_read_b128 v[24:27], v41 offset:34880
	ds_read_b128 v[116:119], v41 offset:44032
	ds_read_b128 v[124:127], v41 offset:46336
	s_waitcnt lgkmcnt(8)
	v_mfma_f32_16x16x32_bf16 v[28:31], v[28:31], v[4:7], 0
	v_exp_f32_e32 v111, v114
	v_cndmask_b32_e64 v145, v220, v236, s[68:69]
	s_waitcnt lgkmcnt(2)
	v_mfma_f32_16x16x32_bf16 v[24:27], v[24:27], v[0:3], v[28:31]
	s_nop 3
	ds_read_b128 v[28:31], v41 offset:44096
	s_waitcnt lgkmcnt(2)
	v_mfma_f32_16x16x32_bf16 v[116:119], v[116:119], v[4:7], 0
	s_waitcnt lgkmcnt(0)
	v_mfma_f32_16x16x32_bf16 v[28:31], v[28:31], v[0:3], v[116:119]
	s_nop 5
	ds_read_b128 v[116:119], v41 offset:37184
	v_mfma_f32_16x16x32_bf16 v[120:123], v[120:123], v[4:7], 0
	s_waitcnt lgkmcnt(0)
	v_mfma_f32_16x16x32_bf16 v[116:119], v[116:119], v[0:3], v[120:123]
	s_nop 5
	ds_read_b128 v[120:123], v41 offset:46400
	v_mfma_f32_16x16x32_bf16 v[124:127], v[124:127], v[4:7], 0
	s_waitcnt lgkmcnt(0)
	v_mfma_f32_16x16x32_bf16 v[120:123], v[120:123], v[0:3], v[124:127]
	s_nop 5
	ds_read_b128 v[124:127], v41 offset:39488
	v_mfma_f32_16x16x32_bf16 v[128:131], v[128:131], v[4:7], 0
	s_waitcnt lgkmcnt(0)
	v_mfma_f32_16x16x32_bf16 v[124:127], v[124:127], v[0:3], v[128:131]
	s_nop 5
	ds_read_b128 v[128:131], v41 offset:48704
	v_mfma_f32_16x16x32_bf16 v[132:135], v[132:135], v[4:7], 0
	s_waitcnt lgkmcnt(0)
	v_mfma_f32_16x16x32_bf16 v[128:131], v[128:131], v[0:3], v[132:135]
	s_nop 5
	ds_read_b128 v[132:135], v41 offset:41792
	v_mfma_f32_16x16x32_bf16 v[136:139], v[136:139], v[4:7], 0
	s_waitcnt lgkmcnt(0)
	v_mfma_f32_16x16x32_bf16 v[132:135], v[132:135], v[0:3], v[136:139]
	s_nop 5
	ds_read_b128 v[136:139], v41 offset:51008
	v_mfma_f32_16x16x32_bf16 v[4:7], v[140:143], v[4:7], 0
	s_waitcnt lgkmcnt(0)
	v_mfma_f32_16x16x32_bf16 v[0:3], v[136:139], v[0:3], v[4:7]
	s_nop 5
	v_ldexp_f32 v6, v111, v115
	v_ldexp_f32 v4, v110, v112
	v_pk_mul_f32 v[110:111], v[6:7], v[128:129] op_sel_hi:[0,1]
	v_pk_mul_f32 v[0:1], v[6:7], v[0:1] op_sel_hi:[0,1]
	v_pk_fma_f32 v[0:1], v[4:5], v[132:133], v[0:1] op_sel_hi:[0,1,1]
	v_pk_add_f32 v[0:1], v[20:21], v[0:1]
	v_pk_mul_f32 v[20:21], v[6:7], v[122:123] op_sel_hi:[0,1]
	v_pk_fma_f32 v[20:21], v[4:5], v[118:119], v[20:21] op_sel_hi:[0,1,1]
	v_pk_add_f32 v[14:15], v[14:15], v[20:21]
	v_pk_mul_f32 v[20:21], v[6:7], v[120:121] op_sel_hi:[0,1]
	v_pk_fma_f32 v[110:111], v[4:5], v[124:125], v[110:111] op_sel_hi:[0,1,1]
	v_pk_fma_f32 v[20:21], v[4:5], v[116:117], v[20:21] op_sel_hi:[0,1,1]
	v_pk_add_f32 v[16:17], v[16:17], v[110:111]
	v_pk_mul_f32 v[110:111], v[6:7], v[130:131] op_sel_hi:[0,1]
	v_pk_mul_f32 v[2:3], v[6:7], v[2:3] op_sel_hi:[0,1]
	v_pk_add_f32 v[12:13], v[12:13], v[20:21]
	v_pk_mul_f32 v[20:21], v[6:7], v[30:31] op_sel_hi:[0,1]
	v_pk_mul_f32 v[6:7], v[6:7], v[28:29] op_sel_hi:[0,1]
	v_pk_fma_f32 v[110:111], v[4:5], v[126:127], v[110:111] op_sel_hi:[0,1,1]
	v_pk_fma_f32 v[2:3], v[4:5], v[134:135], v[2:3] op_sel_hi:[0,1,1]
	v_pk_fma_f32 v[20:21], v[4:5], v[26:27], v[20:21] op_sel_hi:[0,1,1]
	v_pk_fma_f32 v[4:5], v[4:5], v[24:25], v[6:7] op_sel_hi:[0,1,1]
	v_pk_add_f32 v[4:5], v[8:9], v[4:5]
	v_pk_add_f32 v[10:11], v[10:11], v[20:21]
	v_add_f32_e32 v6, 0, v4
	v_add_f32_e32 v6, v5, v6
	v_add_f32_e32 v6, v10, v6
	v_add_f32_e32 v6, v11, v6
	v_add_f32_e32 v6, v6, v12
	v_add_f32_e32 v6, v13, v6
	v_add_f32_e32 v6, v14, v6
	v_add_f32_e32 v6, v15, v6
	v_add_f32_e32 v6, v6, v16
	v_pk_add_f32 v[18:19], v[18:19], v[110:111]
	v_add_f32_e32 v6, v17, v6
	v_add_f32_e32 v6, v18, v6
	v_add_f32_e32 v6, v19, v6
	v_add_f32_e32 v6, v6, v0
	v_pk_add_f32 v[2:3], v[22:23], v[2:3]
	v_add_f32_e32 v6, v1, v6
	v_add_f32_e32 v6, v2, v6
	v_lshlrev_b32_e32 v110, 2, v144
	v_add_f32_e32 v6, v3, v6
	ds_bpermute_b32 v7, v110, v6
	v_lshlrev_b32_e32 v111, 2, v145
	s_waitcnt lgkmcnt(0)
	v_add_f32_e32 v6, v6, v7
	ds_bpermute_b32 v7, v111, v6
	s_waitcnt lgkmcnt(0)
	v_add_f32_e32 v6, v6, v7
	v_mul_f32_e32 v6, 0x3c800000, v6
	v_pk_add_f32 v[20:21], v[4:5], v[6:7] op_sel_hi:[1,0] neg_lo:[0,1] neg_hi:[0,1]
	v_pk_add_f32 v[22:23], v[10:11], v[6:7] op_sel_hi:[1,0] neg_lo:[0,1] neg_hi:[0,1]
	v_pk_mul_f32 v[4:5], v[20:21], v[20:21]
	v_pk_mul_f32 v[8:9], v[22:23], v[22:23]
	v_add_f32_e32 v4, v4, v5
	v_pk_add_f32 v[12:13], v[12:13], v[6:7] op_sel_hi:[1,0] neg_lo:[0,1] neg_hi:[0,1]
	v_add_f32_e32 v4, v8, v4
	v_pk_mul_f32 v[10:11], v[12:13], v[12:13]
	v_add_f32_e32 v4, v9, v4
	v_pk_add_f32 v[14:15], v[14:15], v[6:7] op_sel_hi:[1,0] neg_lo:[0,1] neg_hi:[0,1]
	v_add_f32_e32 v4, v10, v4
	v_pk_mul_f32 v[24:25], v[14:15], v[14:15]
	v_add_f32_e32 v4, v11, v4
	v_pk_add_f32 v[16:17], v[16:17], v[6:7] op_sel_hi:[1,0] neg_lo:[0,1] neg_hi:[0,1]
	v_add_f32_e32 v4, v24, v4
	v_pk_add_f32 v[26:27], v[0:1], v[6:7] op_sel_hi:[1,0] neg_lo:[0,1] neg_hi:[0,1]
	v_pk_add_f32 v[28:29], v[2:3], v[6:7] op_sel_hi:[1,0] neg_lo:[0,1] neg_hi:[0,1]
	v_pk_add_f32 v[18:19], v[18:19], v[6:7] op_sel_hi:[1,0] neg_lo:[0,1] neg_hi:[0,1]
	v_pk_mul_f32 v[6:7], v[16:17], v[16:17]
	v_add_f32_e32 v4, v25, v4
	v_add_f32_e32 v4, v6, v4
	v_pk_mul_f32 v[30:31], v[18:19], v[18:19]
	v_add_f32_e32 v4, v7, v4
	v_add_f32_e32 v4, v30, v4
	v_pk_mul_f32 v[0:1], v[26:27], v[26:27]
	v_add_f32_e32 v4, v31, v4
	v_add_f32_e32 v0, v0, v4
	v_pk_mul_f32 v[2:3], v[28:29], v[28:29]
	v_add_f32_e32 v0, v1, v0
	v_add_f32_e32 v0, v2, v0
	v_add_f32_e32 v0, v3, v0
	ds_bpermute_b32 v1, v110, v0
	v_lshlrev_b64 v[30:31], 1, v[192:193]
	s_waitcnt lgkmcnt(0)
	v_add_f32_e32 v0, v0, v1
	ds_bpermute_b32 v1, v111, v0
	v_lshl_add_u64 v[110:111], v[192:193], 2, s[92:93]
	s_waitcnt lgkmcnt(0)
	v_add_f32_e32 v0, v0, v1
	v_fmamk_f32 v0, v0, 0x3c800000, v194
	v_mul_f32_e32 v1, 0x4b800000, v0
	v_cmp_gt_f32_e64 s[68:69], s0, v0
	v_readlane_b32 s0, v253, 0
	s_add_i32 s97, s97, s0
	v_cndmask_b32_e64 v0, v0, v1, s[68:69]
	v_rsq_f32_e32 v0, v0
	s_cmpk_gt_i32 s97, 0x9ff
	v_mul_f32_e32 v1, 0x45800000, v0
	v_cndmask_b32_e64 v24, v0, v1, s[68:69]
	v_lshl_add_u64 v[0:1], s[2:3], 0, v[36:37]
	v_lshl_add_u64 v[36:37], v[0:1], 0, v[30:31]
	v_mov_b32_e32 v0, v184
	v_mov_b32_e32 v1, v185
	v_mov_b32_e32 v2, v186
	v_mov_b32_e32 v3, v187
	v_mov_b32_e32 v4, v208
	v_mov_b32_e32 v5, v209
	v_mov_b32_e32 v6, v210
	v_mov_b32_e32 v7, v211
	v_mov_b32_e32 v8, v212
	v_mov_b32_e32 v9, v213
	v_mov_b32_e32 v10, v214
	v_mov_b32_e32 v11, v215
	v_readlane_b32 s2, v254, 21
	v_readlane_b32 s3, v254, 22
	v_lshlrev_b32_e32 v112, 16, v0
	v_and_b32_e32 v113, 0xffff0000, v0
	v_lshlrev_b32_e32 v114, 16, v1
	v_and_b32_e32 v115, 0xffff0000, v1
	v_lshlrev_b32_e32 v116, 16, v2
	v_and_b32_e32 v117, 0xffff0000, v2
	v_lshlrev_b32_e32 v118, 16, v3
	v_and_b32_e32 v119, 0xffff0000, v3
	v_pk_mul_f32 v[0:1], v[20:21], v[24:25] op_sel_hi:[1,0]
	v_pk_mul_f32 v[2:3], v[22:23], v[24:25] op_sel_hi:[1,0]
	v_pk_mul_f32 v[0:1], v[4:5], v[0:1]
	v_pk_mul_f32 v[2:3], v[6:7], v[2:3]
	v_pk_mul_f32 v[0:1], v[0:1], v[112:113]
	v_pk_mul_f32 v[2:3], v[2:3], v[114:115]
	v_cvt_pk_bf16_f32 v0, v0, v1
	v_cvt_pk_bf16_f32 v1, v2, v3
	v_pk_mul_f32 v[2:3], v[12:13], v[24:25] op_sel_hi:[1,0]
	v_pk_mul_f32 v[4:5], v[14:15], v[24:25] op_sel_hi:[1,0]
	v_pk_mul_f32 v[2:3], v[8:9], v[2:3]
	v_pk_mul_f32 v[4:5], v[10:11], v[4:5]
	v_lshl_add_u64 v[34:35], s[2:3], 0, v[34:35]
	v_pk_mul_f32 v[2:3], v[2:3], v[116:117]
	v_pk_mul_f32 v[4:5], v[4:5], v[118:119]
	v_lshl_add_u64 v[30:31], v[34:35], 0, v[30:31]
	v_cvt_pk_bf16_f32 v2, v2, v3
	v_cvt_pk_bf16_f32 v3, v4, v5
	global_store_dwordx4 v[30:31], v[0:3], off
	s_nop 1
	v_mov_b32_e32 v0, v188
	v_mov_b32_e32 v1, v189
	v_mov_b32_e32 v2, v190
	v_mov_b32_e32 v3, v191
	s_nop 0
	v_mov_b32_e32 v4, v216
	v_mov_b32_e32 v5, v217
	v_mov_b32_e32 v6, v218
	v_mov_b32_e32 v7, v219
	v_mov_b32_e32 v8, v244
	v_mov_b32_e32 v9, v245
	v_mov_b32_e32 v10, v246
	v_mov_b32_e32 v11, v247
	v_pk_mul_f32 v[14:15], v[16:17], v[24:25] op_sel_hi:[1,0]
	v_lshlrev_b32_e32 v12, 16, v0
	v_pk_mul_f32 v[4:5], v[4:5], v[14:15]
	v_and_b32_e32 v13, 0xffff0000, v0
	v_pk_mul_f32 v[4:5], v[4:5], v[12:13]
	v_pk_mul_f32 v[12:13], v[18:19], v[24:25] op_sel_hi:[1,0]
	v_cvt_pk_bf16_f32 v0, v4, v5
	v_lshlrev_b32_e32 v4, 16, v1
	v_pk_mul_f32 v[6:7], v[6:7], v[12:13]
	v_and_b32_e32 v5, 0xffff0000, v1
	v_pk_mul_f32 v[4:5], v[6:7], v[4:5]
	v_pk_mul_f32 v[6:7], v[26:27], v[24:25] op_sel_hi:[1,0]
	v_cvt_pk_bf16_f32 v1, v4, v5
	v_lshlrev_b32_e32 v4, 16, v2
	v_and_b32_e32 v5, 0xffff0000, v2
	v_pk_mul_f32 v[6:7], v[8:9], v[6:7]
	s_nop 0
	v_pk_mul_f32 v[4:5], v[6:7], v[4:5]
	v_pk_mul_f32 v[6:7], v[28:29], v[24:25] op_sel_hi:[1,0]
	v_cvt_pk_bf16_f32 v2, v4, v5
	v_lshlrev_b32_e32 v4, 16, v3
	v_and_b32_e32 v5, 0xffff0000, v3
	v_pk_mul_f32 v[6:7], v[10:11], v[6:7]
	s_nop 0
	v_pk_mul_f32 v[4:5], v[6:7], v[4:5]
	s_nop 0
	v_cvt_pk_bf16_f32 v3, v4, v5
	global_store_dwordx4 v[30:31], v[0:3], off offset:64
	s_barrier
	s_cbranch_scc1 .LBB0_873

.LBB0_1010:
	v_add_u32_e32 v16, 0xffff0000, v36
	v_ashrrev_i32_e32 v37, 31, v36
	v_lshrrev_b32_e32 v16, 13, v16
	v_lshlrev_b64 v[20:21], 11, v[36:37]
	v_cmp_gt_i32_e32 vcc, s14, v92
	v_add_u32_e32 v16, 16, v16
	v_ashrrev_i32_e32 v17, 11, v92
	v_lshl_add_u64 v[22:23], v[32:33], 0, v[20:21]
	v_cndmask_b32_e32 v24, v16, v17, vcc
	global_load_dwordx4 v[112:115], v[22:23], off
	global_load_dwordx4 v[116:119], v[22:23], off offset:1024
	global_load_dwordx4 v[120:123], v[22:23], off offset:2048
	global_load_dwordx4 v[124:127], v[22:23], off offset:3072
	v_add_u32_e32 v128, s17, v24
	v_mul_hi_i32_i24_e32 v129, 0x6000, v128
	v_mul_i32_i24_e32 v128, 0x6000, v128
	v_mov_b32_e32 v138, v38
	v_mov_b32_e32 v139, v193
	v_lshl_add_u64 v[128:129], s[12:13], 0, v[128:129]
	v_lshl_add_u64 v[130:131], v[128:129], 0, s[18:19]
	v_lshl_add_u64 v[132:133], v[128:129], 0, v[192:193]
	v_lshl_add_u64 v[134:135], v[130:131], 0, v[192:193]
	v_lshl_add_u64 v[136:137], v[130:131], 0, v[138:139]
	global_load_dwordx4 v[140:143], v[132:133], off offset:16
	global_load_dwordx4 v[144:147], v[132:133], off
	global_load_dwordx4 v[148:151], v[134:135], off offset:16
	global_load_dwordx4 v[152:155], v[134:135], off
	global_load_dwordx4 v[156:159], v[132:133], off offset:2064
	global_load_dwordx4 v[160:163], v[132:133], off offset:2048
	global_load_dwordx4 v[164:167], v[136:137], off offset:16
	global_load_dwordx4 v[168:171], v[136:137], off
	v_mov_b32_e32 v39, v193
	v_lshl_add_u64 v[82:83], v[34:35], 0, v[20:21]
	v_add_u32_e32 v37, 64, v242
	v_cmp_lt_i32_e32 vcc, v236, v37
	v_add_u32_e32 v92, s10, v92
	s_waitcnt vmcnt(11)
	v_lshlrev_b32_e32 v70, 16, v112
	v_and_b32_e32 v71, 0xffff0000, v112
	v_lshlrev_b32_e32 v68, 16, v113
	v_and_b32_e32 v69, 0xffff0000, v113
	v_lshlrev_b32_e32 v66, 16, v114
	v_and_b32_e32 v67, 0xffff0000, v114
	v_lshlrev_b32_e32 v64, 16, v115
	v_and_b32_e32 v65, 0xffff0000, v115
	v_mov_b32_e32 v84, v71
	v_mov_b32_e32 v85, v67
	v_pk_mul_f32 v[84:85], v[84:85], v[84:85]
	s_waitcnt vmcnt(10)
	v_lshlrev_b32_e32 v62, 16, v116
	v_and_b32_e32 v63, 0xffff0000, v116
	v_lshlrev_b32_e32 v60, 16, v117
	v_and_b32_e32 v61, 0xffff0000, v117
	v_lshlrev_b32_e32 v58, 16, v118
	v_and_b32_e32 v59, 0xffff0000, v118
	v_lshlrev_b32_e32 v56, 16, v119
	v_and_b32_e32 v57, 0xffff0000, v119
	v_mov_b32_e32 v90, v60
	v_mov_b32_e32 v91, v56
	s_waitcnt vmcnt(9)
	v_lshlrev_b32_e32 v54, 16, v120
	v_and_b32_e32 v55, 0xffff0000, v120
	v_lshlrev_b32_e32 v52, 16, v121
	v_and_b32_e32 v53, 0xffff0000, v121
	v_lshlrev_b32_e32 v50, 16, v122
	v_and_b32_e32 v51, 0xffff0000, v122
	v_lshlrev_b32_e32 v48, 16, v123
	v_and_b32_e32 v49, 0xffff0000, v123
	v_mov_b32_e32 v104, v55
	v_mov_b32_e32 v105, v51
	v_mov_b32_e32 v102, v54
	v_mov_b32_e32 v103, v50
	v_pk_mul_f32 v[104:105], v[104:105], v[104:105]
	s_waitcnt vmcnt(8)
	v_lshlrev_b32_e32 v46, 16, v124
	v_and_b32_e32 v47, 0xffff0000, v124
	v_add_u32_e32 v16, s17, v24
	v_lshlrev_b32_e32 v44, 16, v125
	v_and_b32_e32 v45, 0xffff0000, v125
	v_mul_hi_i32_i24_e32 v17, 0x6000, v16
	v_mul_i32_i24_e32 v16, 0x6000, v16
	v_lshl_add_u64 v[16:17], s[12:13], 0, v[16:17]
	v_lshlrev_b32_e32 v42, 16, v126
	v_and_b32_e32 v43, 0xffff0000, v126
	v_lshlrev_b32_e32 v40, 16, v127
	v_and_b32_e32 v41, 0xffff0000, v127
	v_lshl_add_u64 v[18:19], v[16:17], 0, s[18:19]
	v_lshl_add_u64 v[74:75], v[16:17], 0, v[192:193]
	v_lshl_add_u64 v[28:29], v[18:19], 0, v[192:193]
	v_lshl_add_u64 v[78:79], v[18:19], 0, v[38:39]
	s_waitcnt vmcnt(4)
	v_mov_b32_e32 v16, v140
	v_mov_b32_e32 v17, v141
	v_mov_b32_e32 v18, v142
	v_mov_b32_e32 v19, v143
	v_mov_b32_e32 v24, v144
	v_mov_b32_e32 v25, v145
	v_mov_b32_e32 v26, v146
	v_mov_b32_e32 v27, v147
	v_mov_b32_e32 v20, v148
	v_mov_b32_e32 v21, v149
	v_mov_b32_e32 v22, v150
	v_mov_b32_e32 v23, v151
	s_nop 0
	v_mov_b32_e32 v28, v152
	v_mov_b32_e32 v29, v153
	v_mov_b32_e32 v30, v154
	v_mov_b32_e32 v31, v155
	v_pk_fma_f32 v[102:103], v[102:103], v[102:103], v[104:105]
	v_mov_b32_e32 v106, v47
	v_mov_b32_e32 v107, v43
	v_mov_b32_e32 v104, v46
	v_mov_b32_e32 v105, v42
	v_pk_mul_f32 v[106:107], v[106:107], v[106:107]
	v_cndmask_b32_e32 v39, v220, v236, vcc
	v_pk_fma_f32 v[104:105], v[104:105], v[104:105], v[106:107]
	v_lshlrev_b32_e32 v39, 2, v39
	v_cmp_lt_i32_e32 vcc, v237, v37
	v_pk_add_f32 v[72:73], v[20:21], 1.0 op_sel_hi:[1,0]
	v_pk_add_f32 v[76:77], v[30:31], 1.0 op_sel_hi:[1,0]
	v_mov_b32_e32 v30, v70
	v_mov_b32_e32 v31, v66
	v_mov_b32_e32 v20, v68
	v_mov_b32_e32 v21, v64
	v_pk_fma_f32 v[30:31], v[30:31], v[30:31], v[84:85]
	v_pk_add_f32 v[80:81], v[28:29], 1.0 op_sel_hi:[1,0]
	v_mov_b32_e32 v28, v69
	v_mov_b32_e32 v29, v65
	v_pk_fma_f32 v[20:21], v[20:21], v[20:21], v[30:31]
	v_pk_add_f32 v[84:85], v[22:23], 1.0 op_sel_hi:[1,0]
	v_pk_fma_f32 v[88:89], v[28:29], v[28:29], v[20:21]
	s_waitcnt vmcnt(0)
	v_mov_b32_e32 v20, v156
	v_mov_b32_e32 v21, v157
	v_mov_b32_e32 v22, v158
	v_mov_b32_e32 v23, v159
	v_mov_b32_e32 v28, v160
	v_mov_b32_e32 v29, v161
	v_mov_b32_e32 v30, v162
	v_mov_b32_e32 v31, v163
	v_mov_b32_e32 v94, v164
	v_mov_b32_e32 v95, v165
	v_mov_b32_e32 v96, v166
	v_mov_b32_e32 v97, v167
	v_mov_b32_e32 v98, v168
	v_mov_b32_e32 v99, v169
	v_mov_b32_e32 v100, v170
	v_mov_b32_e32 v101, v171
	v_cndmask_b32_e32 v93, v220, v237, vcc
	v_lshlrev_b32_e32 v93, 2, v93
	v_cmp_lt_i32_e32 vcc, v238, v37
	v_pk_add_f32 v[74:75], v[94:95], 1.0 op_sel_hi:[1,0]
	v_pk_add_f32 v[78:79], v[100:101], 1.0 op_sel_hi:[1,0]
	v_mov_b32_e32 v100, v63
	v_mov_b32_e32 v101, v59
	v_pk_add_f32 v[86:87], v[98:99], 1.0 op_sel_hi:[1,0]
	v_mov_b32_e32 v98, v62
	v_mov_b32_e32 v99, v58
	v_pk_mul_f32 v[100:101], v[100:101], v[100:101]
	v_mov_b32_e32 v94, v61
	v_pk_fma_f32 v[98:99], v[98:99], v[98:99], v[100:101]
	v_mov_b32_e32 v100, v53
	v_pk_fma_f32 v[90:91], v[90:91], v[90:91], v[98:99]
	v_mov_b32_e32 v98, v52
	v_mov_b32_e32 v99, v48
	v_mov_b32_e32 v101, v49
	v_pk_fma_f32 v[98:99], v[98:99], v[98:99], v[102:103]
	v_mov_b32_e32 v95, v57
	v_pk_fma_f32 v[98:99], v[100:101], v[100:101], v[98:99]
	v_mov_b32_e32 v100, v44
	v_mov_b32_e32 v101, v40
	v_mov_b32_e32 v102, v45
	v_mov_b32_e32 v103, v41
	v_pk_fma_f32 v[100:101], v[100:101], v[100:101], v[104:105]
	v_pk_fma_f32 v[90:91], v[94:95], v[94:95], v[90:91]
	v_pk_fma_f32 v[100:101], v[102:103], v[102:103], v[100:101]
	v_mov_b32_e32 v102, v98
	v_mov_b32_e32 v103, v88
	v_mov_b32_e32 v88, v99
	v_pk_add_f32 v[88:89], v[102:103], v[88:89]
	v_mov_b32_e32 v98, v100
	v_mov_b32_e32 v99, v90
	v_pk_add_f32 v[88:89], v[88:89], v[98:99]
	v_mov_b32_e32 v90, v101
	v_pk_add_f32 v[88:89], v[88:89], v[90:91]
	ds_bpermute_b32 v91, v39, v89
	ds_bpermute_b32 v90, v39, v88
	v_cndmask_b32_e32 v94, v220, v238, vcc
	v_lshlrev_b32_e32 v108, 2, v94
	v_cmp_lt_i32_e32 vcc, v239, v37
	s_waitcnt lgkmcnt(0)
	v_pk_add_f32 v[88:89], v[88:89], v[90:91]
	ds_bpermute_b32 v91, v93, v89
	ds_bpermute_b32 v90, v93, v88
	v_cndmask_b32_e32 v94, v220, v239, vcc
	v_lshlrev_b32_e32 v109, 2, v94
	v_cmp_lt_i32_e32 vcc, v240, v37
	s_waitcnt lgkmcnt(0)
	v_pk_add_f32 v[88:89], v[88:89], v[90:91]
	ds_bpermute_b32 v91, v108, v89
	ds_bpermute_b32 v90, v108, v88
	v_cndmask_b32_e32 v94, v220, v240, vcc
	v_lshlrev_b32_e32 v110, 2, v94
	v_cmp_lt_i32_e32 vcc, v241, v37
	v_pk_add_f32 v[94:95], v[96:97], 1.0 op_sel_hi:[1,0]
	s_waitcnt lgkmcnt(0)
	v_pk_add_f32 v[88:89], v[88:89], v[90:91]
	ds_bpermute_b32 v91, v109, v89
	ds_bpermute_b32 v90, v109, v88
	v_cndmask_b32_e32 v37, v220, v241, vcc
	v_lshlrev_b32_e32 v37, 2, v37
	v_add_u32_e32 v96, 1, v36
	v_ashrrev_i32_e32 v97, 31, v96
	s_waitcnt lgkmcnt(0)
	v_pk_add_f32 v[88:89], v[88:89], v[90:91]
	ds_bpermute_b32 v91, v110, v89
	ds_bpermute_b32 v90, v110, v88
	v_lshlrev_b64 v[96:97], 11, v[96:97]
	v_lshl_add_u64 v[96:97], v[34:35], 0, v[96:97]
	v_add_u32_e32 v36, s11, v36
	s_waitcnt lgkmcnt(0)
	v_pk_add_f32 v[88:89], v[88:89], v[90:91]
	ds_bpermute_b32 v91, v37, v89
	ds_bpermute_b32 v90, v37, v88
	s_waitcnt lgkmcnt(0)
	v_pk_add_f32 v[88:89], v[88:89], v[90:91]
	s_nop 0
	v_pk_fma_f32 v[98:99], v[88:89], s[20:21], v[194:195] op_sel_hi:[1,0,0]
	s_nop 0
	v_mul_f32_e32 v37, 0x4b800000, v99
	v_cmp_gt_f32_e64 s[2:3], s15, v99
	v_cmp_gt_f32_e32 vcc, s15, v98
	s_nop 0
	v_cndmask_b32_e64 v37, v99, v37, s[2:3]
	v_rsq_f32_e32 v37, v37
	s_nop 0
	v_mul_f32_e32 v39, 0x45800000, v37
	v_cndmask_b32_e64 v100, v37, v39, s[2:3]
	v_mul_f32_e32 v37, 0x4b800000, v98
	v_cndmask_b32_e32 v37, v98, v37, vcc
	v_rsq_f32_e32 v37, v37
	v_pk_mul_f32 v[64:65], v[100:101], v[64:65] op_sel_hi:[0,1]
	v_pk_mul_f32 v[56:57], v[100:101], v[56:57] op_sel_hi:[0,1]
	v_pk_mul_f32 v[64:65], v[10:11], v[64:65]
	v_pk_mul_f32 v[56:57], v[6:7], v[56:57]
	v_pk_fma_f32 v[64:65], v[84:85], v[64:65], v[18:19]
	v_pk_fma_f32 v[56:57], v[94:95], v[56:57], v[22:23]
	v_mul_f32_e32 v39, 0x45800000, v37
	v_cvt_pk_bf16_f32 v91, v64, v65
	v_cvt_pk_bf16_f32 v65, v56, v57
	v_cndmask_b32_e32 v56, v37, v39, vcc
	v_pk_mul_f32 v[70:71], v[100:101], v[70:71] op_sel_hi:[0,1]
	v_pk_mul_f32 v[68:69], v[100:101], v[68:69] op_sel_hi:[0,1]
	v_pk_mul_f32 v[54:55], v[56:57], v[54:55] op_sel_hi:[0,1]
	v_pk_mul_f32 v[52:53], v[56:57], v[52:53] op_sel_hi:[0,1]
	v_pk_mul_f32 v[70:71], v[0:1], v[70:71]
	v_pk_mul_f32 v[68:69], v[2:3], v[68:69]
	v_pk_mul_f32 v[54:55], v[0:1], v[54:55]
	v_pk_mul_f32 v[52:53], v[2:3], v[52:53]
	v_pk_fma_f32 v[70:71], v[80:81], v[70:71], v[24:25]
	v_pk_fma_f32 v[68:69], v[76:77], v[68:69], v[26:27]
	v_pk_fma_f32 v[24:25], v[80:81], v[54:55], v[24:25]
	v_pk_fma_f32 v[26:27], v[76:77], v[52:53], v[26:27]
	v_pk_mul_f32 v[66:67], v[100:101], v[66:67] op_sel_hi:[0,1]
	v_cvt_pk_bf16_f32 v24, v24, v25
	v_cvt_pk_bf16_f32 v25, v26, v27
	v_pk_mul_f32 v[26:27], v[56:57], v[50:51] op_sel_hi:[0,1]
	v_pk_mul_f32 v[66:67], v[8:9], v[66:67]
	v_pk_mul_f32 v[26:27], v[8:9], v[26:27]
	v_pk_fma_f32 v[66:67], v[72:73], v[66:67], v[16:17]
	v_pk_fma_f32 v[16:17], v[72:73], v[26:27], v[16:17]
	v_pk_mul_f32 v[58:59], v[100:101], v[58:59] op_sel_hi:[0,1]
	v_cvt_pk_bf16_f32 v26, v16, v17
	v_pk_mul_f32 v[16:17], v[56:57], v[48:49] op_sel_hi:[0,1]
	v_pk_mul_f32 v[16:17], v[10:11], v[16:17]
	v_pk_mul_f32 v[58:59], v[4:5], v[58:59]
	v_pk_fma_f32 v[16:17], v[84:85], v[16:17], v[18:19]
	v_pk_mul_f32 v[18:19], v[56:57], v[44:45] op_sel_hi:[0,1]
	v_cvt_pk_bf16_f32 v27, v16, v17
	v_pk_mul_f32 v[16:17], v[56:57], v[46:47] op_sel_hi:[0,1]
	v_pk_mul_f32 v[16:17], v[12:13], v[16:17]
	v_pk_mul_f32 v[18:19], v[14:15], v[18:19]
	v_pk_fma_f32 v[16:17], v[86:87], v[16:17], v[28:29]
	v_pk_fma_f32 v[18:19], v[78:79], v[18:19], v[30:31]
	v_cvt_pk_bf16_f32 v16, v16, v17
	v_cvt_pk_bf16_f32 v17, v18, v19
	v_pk_mul_f32 v[18:19], v[56:57], v[42:43] op_sel_hi:[0,1]
	v_pk_mul_f32 v[18:19], v[4:5], v[18:19]
	v_pk_mul_f32 v[62:63], v[100:101], v[62:63] op_sel_hi:[0,1]
	v_pk_mul_f32 v[60:61], v[100:101], v[60:61] op_sel_hi:[0,1]
	v_pk_fma_f32 v[58:59], v[74:75], v[58:59], v[20:21]
	v_pk_fma_f32 v[18:19], v[74:75], v[18:19], v[20:21]
	v_pk_mul_f32 v[20:21], v[56:57], v[40:41] op_sel_hi:[0,1]
	v_pk_mul_f32 v[62:63], v[12:13], v[62:63]
	v_pk_mul_f32 v[60:61], v[14:15], v[60:61]
	v_pk_mul_f32 v[20:21], v[6:7], v[20:21]
	v_pk_fma_f32 v[62:63], v[86:87], v[62:63], v[28:29]
	v_pk_fma_f32 v[60:61], v[78:79], v[60:61], v[30:31]
	v_pk_fma_f32 v[20:21], v[94:95], v[20:21], v[22:23]
	v_cmp_lt_i32_e32 vcc, s16, v92
	v_cvt_pk_bf16_f32 v88, v70, v71
	v_cvt_pk_bf16_f32 v89, v68, v69
	v_cvt_pk_bf16_f32 v90, v66, v67
	v_cvt_pk_bf16_f32 v62, v62, v63
	v_cvt_pk_bf16_f32 v63, v60, v61
	v_cvt_pk_bf16_f32 v64, v58, v59
	v_cvt_pk_bf16_f32 v18, v18, v19
	v_cvt_pk_bf16_f32 v19, v20, v21
	s_or_b64 s[8:9], vcc, s[8:9]
	global_store_dwordx4 v[82:83], v[88:91], off
	global_store_dwordx4 v[82:83], v[62:65], off offset:1024
	global_store_dwordx4 v[96:97], v[24:27], off
	global_store_dwordx4 v[96:97], v[16:19], off offset:1024
	s_andn2_b64 exec, exec, s[8:9]
	s_cbranch_execnz .LBB0_1010

.LBB0_1030:
	v_or_b32_e32 v140, 0x10000, v144
	v_add_u32_e32 v141, 0x10400, v144
	ds_read_b128 v[146:149], v140
	ds_read_b128 v[150:153], v141
	v_add_u32_e32 v140, 0x10800, v144
	v_add_u32_e32 v141, 0x10c00, v144
	ds_read_b128 v[154:157], v140
	ds_read_b128 v[158:161], v141
	s_add_u32 s22, s20, 0xfffc0080
	s_addc_u32 s23, s21, -1
	s_cmp_eq_u32 s67, 12
	s_cselect_b32 s25, s7, s23
	s_cselect_b32 s24, s9, s22
	s_cselect_b32 s23, s47, s66
	s_cselect_b32 s22, s64, s65
	v_lshl_add_u64 v[140:141], s[20:21], 0, v[136:137]
	s_add_i32 m0, s29, 0xc000
	ds_read_b128 v[162:165], v143
	ds_read_b128 v[166:169], v143 offset:1024
	ds_read_b128 v[170:173], v143 offset:2048
	ds_read_b128 v[174:177], v143 offset:3072
	ds_read_b128 v[178:181], v143 offset:4096
	ds_read_b128 v[182:185], v143 offset:5120
	ds_read_b128 v[186:189], v143 offset:6144
	ds_read_b128 v[206:209], v143 offset:7168
	global_load_lds_dwordx4 v[140:141], off
	v_lshl_add_u64 v[140:141], s[20:21], 0, v[138:139]
	s_add_i32 m0, s29, 0xe000
	s_nop 0
	global_load_lds_dwordx4 v[140:141], off
	s_waitcnt lgkmcnt(8)
	s_barrier
	s_waitcnt lgkmcnt(0)
	s_setprio 1
	s_waitcnt lgkmcnt(0)
	v_mfma_f32_16x16x32_bf16 v[124:127], v[146:149], v[162:165], v[124:127]
	v_mfma_f32_16x16x32_bf16 v[120:123], v[154:157], v[162:165], v[120:123]
	v_mfma_f32_16x16x32_bf16 v[108:111], v[146:149], v[170:173], v[108:111]
	v_mfma_f32_16x16x32_bf16 v[104:107], v[154:157], v[170:173], v[104:107]
	v_mfma_f32_16x16x32_bf16 v[92:95], v[146:149], v[178:181], v[92:95]
	v_mfma_f32_16x16x32_bf16 v[88:91], v[154:157], v[178:181], v[88:91]
	v_mfma_f32_16x16x32_bf16 v[76:79], v[146:149], v[186:189], v[76:79]
	v_mfma_f32_16x16x32_bf16 v[72:75], v[154:157], v[186:189], v[72:75]
	v_mfma_f32_16x16x32_bf16 v[124:127], v[150:153], v[166:169], v[124:127]
	v_mfma_f32_16x16x32_bf16 v[120:123], v[158:161], v[166:169], v[120:123]
	v_mfma_f32_16x16x32_bf16 v[108:111], v[150:153], v[174:177], v[108:111]
	v_mfma_f32_16x16x32_bf16 v[104:107], v[158:161], v[174:177], v[104:107]
	v_mfma_f32_16x16x32_bf16 v[92:95], v[150:153], v[182:185], v[92:95]
	v_mfma_f32_16x16x32_bf16 v[88:91], v[158:161], v[182:185], v[88:91]
	v_mfma_f32_16x16x32_bf16 v[76:79], v[150:153], v[206:209], v[76:79]
	v_mfma_f32_16x16x32_bf16 v[72:75], v[158:161], v[206:209], v[72:75]
	s_setprio 0
	s_barrier
	v_or_b32_e32 v140, 0x14000, v144
	v_add_u32_e32 v141, 0x14400, v144
	ds_read_b128 v[210:213], v140
	ds_read_b128 v[214:217], v141
	v_add_u32_e32 v140, 0x14800, v144
	v_add_u32_e32 v141, 0x14c00, v144
	s_mov_b32 m0, s19
	ds_read_b128 v[244:247], v140
	ds_read_b128 v[248:251], v141
	v_lshl_add_u64 v[140:141], s[22:23], 0, v[132:133]
	global_load_lds_dwordx4 v[140:141], off
	v_lshl_add_u64 v[190:191], s[22:23], 0, v[128:129]
	s_mov_b32 m0, s31
	s_nop 0
	global_load_lds_dwordx4 v[190:191], off
	s_barrier
	s_waitcnt lgkmcnt(0)
	s_setprio 1
	s_waitcnt lgkmcnt(0)
	v_mfma_f32_16x16x32_bf16 v[116:119], v[210:213], v[162:165], v[116:119]
	v_mfma_f32_16x16x32_bf16 v[112:115], v[244:247], v[162:165], v[112:115]
	v_mfma_f32_16x16x32_bf16 v[100:103], v[210:213], v[170:173], v[100:103]
	v_mfma_f32_16x16x32_bf16 v[96:99], v[244:247], v[170:173], v[96:99]
	v_mfma_f32_16x16x32_bf16 v[84:87], v[210:213], v[178:181], v[84:87]
	v_mfma_f32_16x16x32_bf16 v[80:83], v[244:247], v[178:181], v[80:83]
	v_mfma_f32_16x16x32_bf16 v[68:71], v[210:213], v[186:189], v[68:71]
	v_mfma_f32_16x16x32_bf16 v[64:67], v[244:247], v[186:189], v[64:67]
	v_mfma_f32_16x16x32_bf16 v[116:119], v[214:217], v[166:169], v[116:119]
	v_mfma_f32_16x16x32_bf16 v[112:115], v[248:251], v[166:169], v[112:115]
	v_mfma_f32_16x16x32_bf16 v[100:103], v[214:217], v[174:177], v[100:103]
	v_mfma_f32_16x16x32_bf16 v[96:99], v[248:251], v[174:177], v[96:99]
	v_mfma_f32_16x16x32_bf16 v[84:87], v[214:217], v[182:185], v[84:87]
	v_mfma_f32_16x16x32_bf16 v[80:83], v[248:251], v[182:185], v[80:83]
	v_mfma_f32_16x16x32_bf16 v[68:71], v[214:217], v[206:209], v[68:71]
	v_mfma_f32_16x16x32_bf16 v[64:67], v[248:251], v[206:209], v[64:67]
	s_setprio 0
	s_mov_b32 m0, s29
	v_lshl_add_u64 v[218:219], s[24:25], 0, v[134:135]
	s_barrier
	ds_read_b128 v[162:165], v143 offset:16384
	ds_read_b128 v[166:169], v143 offset:17408
	ds_read_b128 v[170:173], v143 offset:18432
	ds_read_b128 v[174:177], v143 offset:19456
	ds_read_b128 v[178:181], v143 offset:20480
	ds_read_b128 v[182:185], v143 offset:21504
	ds_read_b128 v[186:189], v143 offset:22528
	ds_read_b128 v[206:209], v143 offset:23552
	global_load_lds_dwordx4 v[218:219], off
	v_lshl_add_u64 v[228:229], s[24:25], 0, v[130:131]
	s_mov_b32 m0, s34
	s_nop 0
	global_load_lds_dwordx4 v[228:229], off
	s_barrier
	s_waitcnt lgkmcnt(0)
	s_setprio 1
	s_waitcnt lgkmcnt(0)
	v_mfma_f32_16x16x32_bf16 v[60:63], v[146:149], v[162:165], v[60:63]
	v_mfma_f32_16x16x32_bf16 v[56:59], v[154:157], v[162:165], v[56:59]
	v_mfma_f32_16x16x32_bf16 v[44:47], v[146:149], v[170:173], v[44:47]
	v_mfma_f32_16x16x32_bf16 v[40:43], v[154:157], v[170:173], v[40:43]
	v_mfma_f32_16x16x32_bf16 v[28:31], v[146:149], v[178:181], v[28:31]
	v_mfma_f32_16x16x32_bf16 v[24:27], v[154:157], v[178:181], v[24:27]
	v_mfma_f32_16x16x32_bf16 v[12:15], v[146:149], v[186:189], v[12:15]
	v_mfma_f32_16x16x32_bf16 v[8:11], v[154:157], v[186:189], v[8:11]
	v_mfma_f32_16x16x32_bf16 v[60:63], v[150:153], v[166:169], v[60:63]
	v_mfma_f32_16x16x32_bf16 v[56:59], v[158:161], v[166:169], v[56:59]
	v_mfma_f32_16x16x32_bf16 v[44:47], v[150:153], v[174:177], v[44:47]
	v_mfma_f32_16x16x32_bf16 v[40:43], v[158:161], v[174:177], v[40:43]
	v_mfma_f32_16x16x32_bf16 v[28:31], v[150:153], v[182:185], v[28:31]
	v_mfma_f32_16x16x32_bf16 v[24:27], v[158:161], v[182:185], v[24:27]
	v_mfma_f32_16x16x32_bf16 v[12:15], v[150:153], v[206:209], v[12:15]
	v_mfma_f32_16x16x32_bf16 v[8:11], v[158:161], v[206:209], v[8:11]
	s_setprio 0
	s_barrier
	s_add_u32 s68, s22, 0x40000
	s_addc_u32 s69, s23, 0
	s_mov_b32 m0, s35
	v_lshl_add_u64 v[146:147], s[68:69], 0, v[132:133]
	global_load_lds_dwordx4 v[146:147], off
	v_lshl_add_u64 v[146:147], s[68:69], 0, v[128:129]
	s_mov_b32 m0, s36
	s_nop 0
	global_load_lds_dwordx4 v[146:147], off
	s_waitcnt vmcnt(6)
	s_barrier
	s_setprio 1
	v_mfma_f32_16x16x32_bf16 v[52:55], v[210:213], v[162:165], v[52:55]
	v_mfma_f32_16x16x32_bf16 v[48:51], v[244:247], v[162:165], v[48:51]
	v_mfma_f32_16x16x32_bf16 v[36:39], v[210:213], v[170:173], v[36:39]
	v_mfma_f32_16x16x32_bf16 v[32:35], v[244:247], v[170:173], v[32:35]
	v_mfma_f32_16x16x32_bf16 v[20:23], v[210:213], v[178:181], v[20:23]
	v_mfma_f32_16x16x32_bf16 v[16:19], v[244:247], v[178:181], v[16:19]
	v_mfma_f32_16x16x32_bf16 v[4:7], v[210:213], v[186:189], v[4:7]
	v_mfma_f32_16x16x32_bf16 v[0:3], v[244:247], v[186:189], v[0:3]
	v_mfma_f32_16x16x32_bf16 v[52:55], v[214:217], v[166:169], v[52:55]
	v_mfma_f32_16x16x32_bf16 v[48:51], v[248:251], v[166:169], v[48:51]
	v_mfma_f32_16x16x32_bf16 v[36:39], v[214:217], v[174:177], v[36:39]
	v_mfma_f32_16x16x32_bf16 v[32:35], v[248:251], v[174:177], v[32:35]
	v_mfma_f32_16x16x32_bf16 v[20:23], v[214:217], v[182:185], v[20:23]
	v_mfma_f32_16x16x32_bf16 v[16:19], v[248:251], v[182:185], v[16:19]
	v_mfma_f32_16x16x32_bf16 v[4:7], v[214:217], v[206:209], v[4:7]
	v_mfma_f32_16x16x32_bf16 v[0:3], v[248:251], v[206:209], v[0:3]
	s_setprio 0
	v_or_b32_e32 v145, 0x18000, v144
	v_add_u32_e32 v150, 0x18400, v144
	s_barrier
	ds_read_b128 v[146:149], v145
	ds_read_b128 v[150:153], v150
	v_add_u32_e32 v145, 0x18800, v144
	v_add_u32_e32 v158, 0x18c00, v144
	ds_read_b128 v[154:157], v145
	ds_read_b128 v[158:161], v158
	s_add_u32 s24, s24, 0x40000
	s_addc_u32 s25, s25, 0
	s_mov_b32 m0, s37
	v_lshl_add_u64 v[210:211], s[24:25], 0, v[134:135]
	ds_read_b128 v[162:165], v143 offset:32768
	ds_read_b128 v[166:169], v143 offset:33792
	ds_read_b128 v[170:173], v143 offset:34816
	ds_read_b128 v[174:177], v143 offset:35840
	ds_read_b128 v[178:181], v143 offset:36864
	ds_read_b128 v[182:185], v143 offset:37888
	ds_read_b128 v[186:189], v143 offset:38912
	ds_read_b128 v[206:209], v143 offset:39936
	global_load_lds_dwordx4 v[210:211], off
	v_lshl_add_u64 v[210:211], s[24:25], 0, v[130:131]
	s_mov_b32 m0, s38
	s_nop 0
	global_load_lds_dwordx4 v[210:211], off
	s_waitcnt lgkmcnt(8)
	s_barrier
	s_waitcnt lgkmcnt(0)
	s_setprio 1
	s_waitcnt lgkmcnt(0)
	v_mfma_f32_16x16x32_bf16 v[124:127], v[146:149], v[162:165], v[124:127]
	v_mfma_f32_16x16x32_bf16 v[120:123], v[154:157], v[162:165], v[120:123]
	v_mfma_f32_16x16x32_bf16 v[108:111], v[146:149], v[170:173], v[108:111]
	v_mfma_f32_16x16x32_bf16 v[104:107], v[154:157], v[170:173], v[104:107]
	v_mfma_f32_16x16x32_bf16 v[92:95], v[146:149], v[178:181], v[92:95]
	v_mfma_f32_16x16x32_bf16 v[88:91], v[154:157], v[178:181], v[88:91]
	v_mfma_f32_16x16x32_bf16 v[76:79], v[146:149], v[186:189], v[76:79]
	v_mfma_f32_16x16x32_bf16 v[72:75], v[154:157], v[186:189], v[72:75]
	v_mfma_f32_16x16x32_bf16 v[124:127], v[150:153], v[166:169], v[124:127]
	v_mfma_f32_16x16x32_bf16 v[120:123], v[158:161], v[166:169], v[120:123]
	v_mfma_f32_16x16x32_bf16 v[108:111], v[150:153], v[174:177], v[108:111]
	v_mfma_f32_16x16x32_bf16 v[104:107], v[158:161], v[174:177], v[104:107]
	v_mfma_f32_16x16x32_bf16 v[92:95], v[150:153], v[182:185], v[92:95]
	v_mfma_f32_16x16x32_bf16 v[88:91], v[158:161], v[182:185], v[88:91]
	v_mfma_f32_16x16x32_bf16 v[76:79], v[150:153], v[206:209], v[76:79]
	v_mfma_f32_16x16x32_bf16 v[72:75], v[158:161], v[206:209], v[72:75]
	s_setprio 0
	s_barrier
	v_or_b32_e32 v145, 0x1c000, v144
	s_mov_b32 m0, s39
	v_add_u32_e32 v201, 0x1c400, v144
	ds_read_b128 v[210:213], v145
	ds_read_b128 v[214:217], v201
	v_add_u32_e32 v145, 0x1c800, v144
	v_lshl_add_u64 v[140:141], v[140:141], 0, s[94:95]
	v_add_u32_e32 v201, 0x1cc00, v144
	ds_read_b128 v[244:247], v145
	ds_read_b128 v[248:251], v201
	global_load_lds_dwordx4 v[140:141], off
	v_lshl_add_u64 v[140:141], v[190:191], 0, s[94:95]
	s_mov_b32 m0, s40
	s_nop 0
	global_load_lds_dwordx4 v[140:141], off
	s_barrier
	s_waitcnt lgkmcnt(0)
	s_setprio 1
	s_waitcnt lgkmcnt(0)
	v_mfma_f32_16x16x32_bf16 v[116:119], v[210:213], v[162:165], v[116:119]
	v_mfma_f32_16x16x32_bf16 v[112:115], v[244:247], v[162:165], v[112:115]
	v_mfma_f32_16x16x32_bf16 v[100:103], v[210:213], v[170:173], v[100:103]
	v_mfma_f32_16x16x32_bf16 v[96:99], v[244:247], v[170:173], v[96:99]
	v_mfma_f32_16x16x32_bf16 v[84:87], v[210:213], v[178:181], v[84:87]
	v_mfma_f32_16x16x32_bf16 v[80:83], v[244:247], v[178:181], v[80:83]
	v_mfma_f32_16x16x32_bf16 v[68:71], v[210:213], v[186:189], v[68:71]
	v_mfma_f32_16x16x32_bf16 v[64:67], v[244:247], v[186:189], v[64:67]
	v_mfma_f32_16x16x32_bf16 v[116:119], v[214:217], v[166:169], v[116:119]
	v_mfma_f32_16x16x32_bf16 v[112:115], v[248:251], v[166:169], v[112:115]
	v_mfma_f32_16x16x32_bf16 v[100:103], v[214:217], v[174:177], v[100:103]
	v_mfma_f32_16x16x32_bf16 v[96:99], v[248:251], v[174:177], v[96:99]
	v_mfma_f32_16x16x32_bf16 v[84:87], v[214:217], v[182:185], v[84:87]
	v_mfma_f32_16x16x32_bf16 v[80:83], v[248:251], v[182:185], v[80:83]
	v_mfma_f32_16x16x32_bf16 v[68:71], v[214:217], v[206:209], v[68:71]
	v_mfma_f32_16x16x32_bf16 v[64:67], v[248:251], v[206:209], v[64:67]
	s_setprio 0
	s_mov_b32 m0, s41
	v_lshl_add_u64 v[140:141], v[218:219], 0, s[94:95]
	s_barrier
	ds_read_b128 v[162:165], v143 offset:49152
	ds_read_b128 v[166:169], v143 offset:50176
	ds_read_b128 v[170:173], v143 offset:51200
	ds_read_b128 v[174:177], v143 offset:52224
	ds_read_b128 v[178:181], v143 offset:53248
	ds_read_b128 v[182:185], v143 offset:54272
	ds_read_b128 v[186:189], v143 offset:55296
	ds_read_b128 v[206:209], v143 offset:56320
	global_load_lds_dwordx4 v[140:141], off
	v_lshl_add_u64 v[140:141], v[228:229], 0, s[94:95]
	s_mov_b32 m0, s42
	s_nop 0
	global_load_lds_dwordx4 v[140:141], off
	s_barrier
	s_waitcnt lgkmcnt(0)
	s_setprio 1
	s_waitcnt lgkmcnt(0)
	v_mfma_f32_16x16x32_bf16 v[60:63], v[146:149], v[162:165], v[60:63]
	v_mfma_f32_16x16x32_bf16 v[56:59], v[154:157], v[162:165], v[56:59]
	v_mfma_f32_16x16x32_bf16 v[44:47], v[146:149], v[170:173], v[44:47]
	v_mfma_f32_16x16x32_bf16 v[40:43], v[154:157], v[170:173], v[40:43]
	v_mfma_f32_16x16x32_bf16 v[28:31], v[146:149], v[178:181], v[28:31]
	v_mfma_f32_16x16x32_bf16 v[24:27], v[154:157], v[178:181], v[24:27]
	v_mfma_f32_16x16x32_bf16 v[12:15], v[146:149], v[186:189], v[12:15]
	v_mfma_f32_16x16x32_bf16 v[8:11], v[154:157], v[186:189], v[8:11]
	v_mfma_f32_16x16x32_bf16 v[60:63], v[150:153], v[166:169], v[60:63]
	v_mfma_f32_16x16x32_bf16 v[56:59], v[158:161], v[166:169], v[56:59]
	v_mfma_f32_16x16x32_bf16 v[44:47], v[150:153], v[174:177], v[44:47]
	v_mfma_f32_16x16x32_bf16 v[40:43], v[158:161], v[174:177], v[40:43]
	v_mfma_f32_16x16x32_bf16 v[28:31], v[150:153], v[182:185], v[28:31]
	v_mfma_f32_16x16x32_bf16 v[24:27], v[158:161], v[182:185], v[24:27]
	v_mfma_f32_16x16x32_bf16 v[12:15], v[150:153], v[206:209], v[12:15]
	v_mfma_f32_16x16x32_bf16 v[8:11], v[158:161], v[206:209], v[8:11]
	s_setprio 0
	s_barrier
	s_add_u32 s22, s22, 0x40080
	s_addc_u32 s23, s23, 0
	s_mov_b32 m0, s43
	v_lshl_add_u64 v[140:141], s[22:23], 0, v[132:133]
	global_load_lds_dwordx4 v[140:141], off
	v_lshl_add_u64 v[140:141], s[22:23], 0, v[128:129]
	s_mov_b32 m0, s44
	s_nop 0
	global_load_lds_dwordx4 v[140:141], off
	s_waitcnt vmcnt(6)
	s_barrier
	s_setprio 1
	v_mfma_f32_16x16x32_bf16 v[52:55], v[210:213], v[162:165], v[52:55]
	v_mfma_f32_16x16x32_bf16 v[48:51], v[244:247], v[162:165], v[48:51]
	v_mfma_f32_16x16x32_bf16 v[36:39], v[210:213], v[170:173], v[36:39]
	v_mfma_f32_16x16x32_bf16 v[32:35], v[244:247], v[170:173], v[32:35]
	v_mfma_f32_16x16x32_bf16 v[20:23], v[210:213], v[178:181], v[20:23]
	v_mfma_f32_16x16x32_bf16 v[16:19], v[244:247], v[178:181], v[16:19]
	v_mfma_f32_16x16x32_bf16 v[4:7], v[210:213], v[186:189], v[4:7]
	v_mfma_f32_16x16x32_bf16 v[0:3], v[244:247], v[186:189], v[0:3]
	v_mfma_f32_16x16x32_bf16 v[52:55], v[214:217], v[166:169], v[52:55]
	v_mfma_f32_16x16x32_bf16 v[48:51], v[248:251], v[166:169], v[48:51]
	v_mfma_f32_16x16x32_bf16 v[36:39], v[214:217], v[174:177], v[36:39]
	v_mfma_f32_16x16x32_bf16 v[32:35], v[248:251], v[174:177], v[32:35]
	v_mfma_f32_16x16x32_bf16 v[20:23], v[214:217], v[182:185], v[20:23]
	v_mfma_f32_16x16x32_bf16 v[16:19], v[248:251], v[182:185], v[16:19]
	v_mfma_f32_16x16x32_bf16 v[4:7], v[214:217], v[206:209], v[4:7]
	v_mfma_f32_16x16x32_bf16 v[0:3], v[248:251], v[206:209], v[0:3]
	s_setprio 0
	s_add_i32 s67, s67, 2
	s_add_u32 s20, s20, 0x100
	s_addc_u32 s21, s21, 0
	s_add_u32 s65, s65, 0x100
	s_addc_u32 s66, s66, 0
	s_cmp_gt_u32 s67, 13
	s_barrier
	s_cbranch_scc0 .LBB0_1030
	v_lshl_add_u32 v140, s18, 8, v142
	v_ashrrev_i32_e32 v141, 31, v140
	v_readlane_b32 s20, v254, 15
	v_lshlrev_b64 v[140:141], 13, v[140:141]
	v_readlane_b32 s21, v254, 16
	s_nop 0
	v_max_f32_e32 v146, 0, v120
	v_lshl_add_u64 v[140:141], s[20:21], 0, v[140:141]
	s_lshl_b32 s20, s46, 8
	v_max_f32_e32 v147, 0, v121
	s_ashr_i32 s21, s20, 31
	v_max_f32_e32 v124, 0, v124
	v_max_f32_e32 v125, 0, v125
	v_max_f32_e32 v126, 0, v126
	v_max_f32_e32 v127, 0, v127
	v_max_f32_e32 v148, 0, v122
	v_lshl_add_u64 v[140:141], s[20:21], 1, v[140:141]
	v_max_f32_e32 v149, 0, v123
	v_pk_mul_f32 v[120:121], v[124:125], v[124:125]
	v_pk_mul_f32 v[122:123], v[126:127], v[126:127]
	v_lshl_add_u64 v[140:141], v[140:141], 0, s[0:1]
	v_cvt_pk_bf16_f32 v120, v120, v121
	v_cvt_pk_bf16_f32 v121, v122, v123
	v_pk_mul_f32 v[122:123], v[146:147], v[146:147]
	v_pk_mul_f32 v[124:125], v[148:149], v[148:149]
	v_lshl_add_u64 v[140:141], v[140:141], 0, v[192:193]
	v_cvt_pk_bf16_f32 v122, v122, v123
	v_cvt_pk_bf16_f32 v123, v124, v125
	global_store_dwordx4 v[140:141], v[120:123], off
	s_nop 1
	v_max_f32_e32 v120, 0, v112
	v_max_f32_e32 v121, 0, v113
	v_max_f32_e32 v116, 0, v116
	v_max_f32_e32 v117, 0, v117
	v_max_f32_e32 v118, 0, v118
	v_max_f32_e32 v119, 0, v119
	v_max_f32_e32 v122, 0, v114
	v_max_f32_e32 v123, 0, v115
	v_pk_mul_f32 v[112:113], v[116:117], v[116:117]
	v_pk_mul_f32 v[114:115], v[118:119], v[118:119]
	v_cvt_pk_bf16_f32 v112, v112, v113
	v_cvt_pk_bf16_f32 v113, v114, v115
	v_pk_mul_f32 v[114:115], v[120:121], v[120:121]
	v_pk_mul_f32 v[116:117], v[122:123], v[122:123]
	v_cvt_pk_bf16_f32 v114, v114, v115
	v_cvt_pk_bf16_f32 v115, v116, v117
	global_store_dwordx4 v[140:141], v[112:115], off offset:256
	s_nop 1
	v_max_f32_e32 v112, 0, v104
	v_max_f32_e32 v113, 0, v105
	v_max_f32_e32 v108, 0, v108
	v_max_f32_e32 v109, 0, v109
	v_max_f32_e32 v110, 0, v110
	v_max_f32_e32 v111, 0, v111
	v_max_f32_e32 v114, 0, v106
	v_max_f32_e32 v115, 0, v107
	v_pk_mul_f32 v[104:105], v[108:109], v[108:109]
	v_pk_mul_f32 v[106:107], v[110:111], v[110:111]
	v_cvt_pk_bf16_f32 v104, v104, v105
	v_cvt_pk_bf16_f32 v105, v106, v107
	v_pk_mul_f32 v[106:107], v[112:113], v[112:113]
	v_pk_mul_f32 v[108:109], v[114:115], v[114:115]
	s_mov_b32 s7, 0x20000
	v_cvt_pk_bf16_f32 v106, v106, v107
	v_cvt_pk_bf16_f32 v107, v108, v109
	v_add_co_u32_e32 v108, vcc, s7, v140
	s_nop 0
	v_addc_co_u32_e32 v109, vcc, 0, v141, vcc
	global_store_dwordx4 v[108:109], v[104:107], off
	s_nop 1
	v_max_f32_e32 v104, 0, v96
	v_max_f32_e32 v105, 0, v97
	v_max_f32_e32 v100, 0, v100
	v_max_f32_e32 v101, 0, v101
	v_max_f32_e32 v102, 0, v102
	v_max_f32_e32 v103, 0, v103
	v_max_f32_e32 v106, 0, v98
	v_max_f32_e32 v107, 0, v99
	v_pk_mul_f32 v[96:97], v[100:101], v[100:101]
	v_pk_mul_f32 v[98:99], v[102:103], v[102:103]
	v_cvt_pk_bf16_f32 v96, v96, v97
	v_cvt_pk_bf16_f32 v97, v98, v99
	v_pk_mul_f32 v[98:99], v[104:105], v[104:105]
	v_pk_mul_f32 v[100:101], v[106:107], v[106:107]
	v_cvt_pk_bf16_f32 v98, v98, v99
	v_cvt_pk_bf16_f32 v99, v100, v101
	global_store_dwordx4 v[108:109], v[96:99], off offset:256
	s_nop 1
	v_max_f32_e32 v96, 0, v88
	v_max_f32_e32 v97, 0, v89
	v_max_f32_e32 v92, 0, v92
	v_max_f32_e32 v93, 0, v93
	v_max_f32_e32 v94, 0, v94
	v_max_f32_e32 v95, 0, v95
	v_max_f32_e32 v98, 0, v90
	v_max_f32_e32 v99, 0, v91
	v_pk_mul_f32 v[88:89], v[92:93], v[92:93]
	v_pk_mul_f32 v[90:91], v[94:95], v[94:95]
	v_cvt_pk_bf16_f32 v88, v88, v89
	v_cvt_pk_bf16_f32 v89, v90, v91
	v_pk_mul_f32 v[90:91], v[96:97], v[96:97]
	v_pk_mul_f32 v[92:93], v[98:99], v[98:99]
	s_mov_b32 s7, 0x40000
	v_cvt_pk_bf16_f32 v90, v90, v91
	v_cvt_pk_bf16_f32 v91, v92, v93
	v_add_co_u32_e32 v92, vcc, s7, v140
	s_nop 0
	v_addc_co_u32_e32 v93, vcc, 0, v141, vcc
	global_store_dwordx4 v[92:93], v[88:91], off
	s_nop 1
	v_max_f32_e32 v88, 0, v80
	v_max_f32_e32 v89, 0, v81
	v_max_f32_e32 v84, 0, v84
	v_max_f32_e32 v85, 0, v85
	v_max_f32_e32 v86, 0, v86
	v_max_f32_e32 v87, 0, v87
	v_max_f32_e32 v90, 0, v82
	v_max_f32_e32 v91, 0, v83
	v_pk_mul_f32 v[80:81], v[84:85], v[84:85]
	v_pk_mul_f32 v[82:83], v[86:87], v[86:87]
	v_cvt_pk_bf16_f32 v80, v80, v81
	v_cvt_pk_bf16_f32 v81, v82, v83
	v_pk_mul_f32 v[82:83], v[88:89], v[88:89]
	v_pk_mul_f32 v[84:85], v[90:91], v[90:91]
	v_cvt_pk_bf16_f32 v82, v82, v83
	v_cvt_pk_bf16_f32 v83, v84, v85
	global_store_dwordx4 v[92:93], v[80:83], off offset:256
	s_nop 1
	v_max_f32_e32 v80, 0, v72
	v_max_f32_e32 v81, 0, v73
	v_max_f32_e32 v76, 0, v76
	v_max_f32_e32 v77, 0, v77
	v_max_f32_e32 v78, 0, v78
	v_max_f32_e32 v79, 0, v79
	v_max_f32_e32 v82, 0, v74
	v_max_f32_e32 v83, 0, v75
	v_pk_mul_f32 v[72:73], v[76:77], v[76:77]
	v_pk_mul_f32 v[74:75], v[78:79], v[78:79]
	v_cvt_pk_bf16_f32 v72, v72, v73
	v_cvt_pk_bf16_f32 v73, v74, v75
	v_pk_mul_f32 v[74:75], v[80:81], v[80:81]
	v_pk_mul_f32 v[76:77], v[82:83], v[82:83]
	s_mov_b32 s7, 0x60000
	v_cvt_pk_bf16_f32 v74, v74, v75
	v_cvt_pk_bf16_f32 v75, v76, v77
	v_add_co_u32_e32 v76, vcc, s7, v140
	s_nop 0
	v_addc_co_u32_e32 v77, vcc, 0, v141, vcc
	global_store_dwordx4 v[76:77], v[72:75], off
	s_nop 1
	v_max_f32_e32 v72, 0, v64
	v_max_f32_e32 v73, 0, v65
	v_max_f32_e32 v68, 0, v68
	v_max_f32_e32 v69, 0, v69
	v_max_f32_e32 v70, 0, v70
	v_max_f32_e32 v71, 0, v71
	v_max_f32_e32 v74, 0, v66
	v_max_f32_e32 v75, 0, v67
	v_pk_mul_f32 v[64:65], v[68:69], v[68:69]
	v_pk_mul_f32 v[66:67], v[70:71], v[70:71]
	v_cvt_pk_bf16_f32 v64, v64, v65
	v_cvt_pk_bf16_f32 v65, v66, v67
	v_pk_mul_f32 v[66:67], v[72:73], v[72:73]
	v_pk_mul_f32 v[68:69], v[74:75], v[74:75]
	v_cvt_pk_bf16_f32 v66, v66, v67
	v_cvt_pk_bf16_f32 v67, v68, v69
	global_store_dwordx4 v[76:77], v[64:67], off offset:256
	s_nop 1
	v_max_f32_e32 v64, 0, v56
	v_max_f32_e32 v65, 0, v57
	v_max_f32_e32 v60, 0, v60
	v_max_f32_e32 v61, 0, v61
	v_max_f32_e32 v62, 0, v62
	v_max_f32_e32 v63, 0, v63
	v_max_f32_e32 v66, 0, v58
	v_max_f32_e32 v67, 0, v59
	v_pk_mul_f32 v[56:57], v[60:61], v[60:61]
	v_pk_mul_f32 v[58:59], v[62:63], v[62:63]
	v_cvt_pk_bf16_f32 v56, v56, v57
	v_cvt_pk_bf16_f32 v57, v58, v59
	v_pk_mul_f32 v[58:59], v[64:65], v[64:65]
	v_pk_mul_f32 v[60:61], v[66:67], v[66:67]
	s_mov_b32 s7, 0x100000
	v_cvt_pk_bf16_f32 v58, v58, v59
	v_cvt_pk_bf16_f32 v59, v60, v61
	v_add_co_u32_e32 v60, vcc, s7, v140
	s_nop 0
	v_addc_co_u32_e32 v61, vcc, 0, v141, vcc
	global_store_dwordx4 v[60:61], v[56:59], off
	s_nop 1
	v_max_f32_e32 v56, 0, v48
	v_max_f32_e32 v57, 0, v49
	v_max_f32_e32 v52, 0, v52
	v_max_f32_e32 v53, 0, v53
	v_max_f32_e32 v54, 0, v54
	v_max_f32_e32 v55, 0, v55
	v_max_f32_e32 v58, 0, v50
	v_max_f32_e32 v59, 0, v51
	v_pk_mul_f32 v[48:49], v[52:53], v[52:53]
	v_pk_mul_f32 v[50:51], v[54:55], v[54:55]
	v_cvt_pk_bf16_f32 v48, v48, v49
	v_cvt_pk_bf16_f32 v49, v50, v51
	v_pk_mul_f32 v[50:51], v[56:57], v[56:57]
	v_pk_mul_f32 v[52:53], v[58:59], v[58:59]
	v_cvt_pk_bf16_f32 v50, v50, v51
	v_cvt_pk_bf16_f32 v51, v52, v53
	global_store_dwordx4 v[60:61], v[48:51], off offset:256
	s_nop 1
	v_max_f32_e32 v48, 0, v40
	v_max_f32_e32 v49, 0, v41
	v_max_f32_e32 v44, 0, v44
	v_max_f32_e32 v45, 0, v45
	v_max_f32_e32 v46, 0, v46
	v_max_f32_e32 v47, 0, v47
	v_max_f32_e32 v50, 0, v42
	v_max_f32_e32 v51, 0, v43
	v_pk_mul_f32 v[40:41], v[44:45], v[44:45]
	v_pk_mul_f32 v[42:43], v[46:47], v[46:47]
	v_cvt_pk_bf16_f32 v40, v40, v41
	v_cvt_pk_bf16_f32 v41, v42, v43
	v_pk_mul_f32 v[42:43], v[48:49], v[48:49]
	v_pk_mul_f32 v[44:45], v[50:51], v[50:51]
	s_mov_b32 s7, 0x120000
	v_cvt_pk_bf16_f32 v42, v42, v43
	v_cvt_pk_bf16_f32 v43, v44, v45
	v_add_co_u32_e32 v44, vcc, s7, v140
	s_nop 0
	v_addc_co_u32_e32 v45, vcc, 0, v141, vcc
	global_store_dwordx4 v[44:45], v[40:43], off
	s_nop 1
	v_max_f32_e32 v40, 0, v32
	v_max_f32_e32 v41, 0, v33
	v_max_f32_e32 v36, 0, v36
	v_max_f32_e32 v37, 0, v37
	v_max_f32_e32 v38, 0, v38
	v_max_f32_e32 v39, 0, v39
	v_max_f32_e32 v42, 0, v34
	v_max_f32_e32 v43, 0, v35
	v_pk_mul_f32 v[32:33], v[36:37], v[36:37]
	v_pk_mul_f32 v[34:35], v[38:39], v[38:39]
	v_cvt_pk_bf16_f32 v32, v32, v33
	v_cvt_pk_bf16_f32 v33, v34, v35
	v_pk_mul_f32 v[34:35], v[40:41], v[40:41]
	v_pk_mul_f32 v[36:37], v[42:43], v[42:43]
	v_cvt_pk_bf16_f32 v34, v34, v35
	v_cvt_pk_bf16_f32 v35, v36, v37
	global_store_dwordx4 v[44:45], v[32:35], off offset:256
	s_nop 1
	v_max_f32_e32 v32, 0, v24
	v_max_f32_e32 v33, 0, v25
	v_max_f32_e32 v28, 0, v28
	v_max_f32_e32 v29, 0, v29
	v_max_f32_e32 v30, 0, v30
	v_max_f32_e32 v31, 0, v31
	v_max_f32_e32 v34, 0, v26
	v_max_f32_e32 v35, 0, v27
	v_pk_mul_f32 v[24:25], v[28:29], v[28:29]
	v_pk_mul_f32 v[26:27], v[30:31], v[30:31]
	v_cvt_pk_bf16_f32 v24, v24, v25
	v_cvt_pk_bf16_f32 v25, v26, v27
	v_pk_mul_f32 v[26:27], v[32:33], v[32:33]
	v_pk_mul_f32 v[28:29], v[34:35], v[34:35]
	s_mov_b32 s7, 0x140000
	v_cvt_pk_bf16_f32 v26, v26, v27
	v_cvt_pk_bf16_f32 v27, v28, v29
	v_add_co_u32_e32 v28, vcc, s7, v140
	s_nop 0
	v_addc_co_u32_e32 v29, vcc, 0, v141, vcc
	global_store_dwordx4 v[28:29], v[24:27], off
	s_nop 1
	v_max_f32_e32 v24, 0, v16
	v_max_f32_e32 v25, 0, v17
	v_max_f32_e32 v20, 0, v20
	v_max_f32_e32 v21, 0, v21
	v_max_f32_e32 v22, 0, v22
	v_max_f32_e32 v23, 0, v23
	v_max_f32_e32 v26, 0, v18
	v_max_f32_e32 v27, 0, v19
	v_pk_mul_f32 v[16:17], v[20:21], v[20:21]
	v_pk_mul_f32 v[18:19], v[22:23], v[22:23]
	v_cvt_pk_bf16_f32 v16, v16, v17
	v_cvt_pk_bf16_f32 v17, v18, v19
	v_pk_mul_f32 v[18:19], v[24:25], v[24:25]
	v_pk_mul_f32 v[20:21], v[26:27], v[26:27]
	v_cvt_pk_bf16_f32 v18, v18, v19
	v_cvt_pk_bf16_f32 v19, v20, v21
	global_store_dwordx4 v[28:29], v[16:19], off offset:256
	s_nop 1
	v_max_f32_e32 v16, 0, v8
	v_max_f32_e32 v17, 0, v9
	v_max_f32_e32 v12, 0, v12
	v_max_f32_e32 v13, 0, v13
	v_max_f32_e32 v14, 0, v14
	v_max_f32_e32 v15, 0, v15
	v_max_f32_e32 v18, 0, v10
	v_max_f32_e32 v19, 0, v11
	v_pk_mul_f32 v[8:9], v[12:13], v[12:13]
	v_pk_mul_f32 v[10:11], v[14:15], v[14:15]
	v_cvt_pk_bf16_f32 v8, v8, v9
	v_cvt_pk_bf16_f32 v9, v10, v11
	v_pk_mul_f32 v[10:11], v[16:17], v[16:17]
	v_pk_mul_f32 v[12:13], v[18:19], v[18:19]
	s_mov_b32 s7, 0x160000
	v_cvt_pk_bf16_f32 v10, v10, v11
	v_cvt_pk_bf16_f32 v11, v12, v13
	v_add_co_u32_e32 v12, vcc, s7, v140
	s_nop 0
	v_addc_co_u32_e32 v13, vcc, 0, v141, vcc
	global_store_dwordx4 v[12:13], v[8:11], off
	s_nop 1
	v_max_f32_e32 v8, 0, v0
	v_max_f32_e32 v9, 0, v1
	v_max_f32_e32 v4, 0, v4
	v_max_f32_e32 v5, 0, v5
	v_max_f32_e32 v6, 0, v6
	v_max_f32_e32 v7, 0, v7
	v_max_f32_e32 v10, 0, v2
	v_max_f32_e32 v11, 0, v3
	v_pk_mul_f32 v[0:1], v[4:5], v[4:5]
	v_pk_mul_f32 v[2:3], v[6:7], v[6:7]
	v_cvt_pk_bf16_f32 v0, v0, v1
	v_cvt_pk_bf16_f32 v1, v2, v3
	v_pk_mul_f32 v[2:3], v[8:9], v[8:9]
	v_pk_mul_f32 v[4:5], v[10:11], v[10:11]
	v_cvt_pk_bf16_f32 v2, v2, v3
	v_cvt_pk_bf16_f32 v3, v4, v5
	global_store_dwordx4 v[12:13], v[0:3], off offset:256
	s_and_b64 vcc, exec, s[2:3]
	s_mov_b32 s46, s6
	s_mov_b32 s18, s8
	s_mov_b64 s[22:23], s[16:17]
	s_mov_b64 s[20:21], s[14:15]
	s_cbranch_vccz .LBB0_1027
	s_waitcnt vmcnt(0)
	s_cmpk_gt_u32 s26, 0xff
	s_cbranch_scc1 .LBB0_1034
	s_barrier

	.amdhsa_kernel _Z16trunk_megakernel6Params
		.amdhsa_group_segment_fixed_size 131072
		.amdhsa_private_segment_fixed_size 0
		.amdhsa_kernarg_size 456
		.amdhsa_user_sgpr_count 2
		.amdhsa_user_sgpr_dispatch_ptr 0
		.amdhsa_user_sgpr_queue_ptr 0
		.amdhsa_user_sgpr_kernarg_segment_ptr 1
		.amdhsa_user_sgpr_dispatch_id 0
		.amdhsa_user_sgpr_kernarg_preload_length 0
		.amdhsa_user_sgpr_kernarg_preload_offset 0
		.amdhsa_user_sgpr_private_segment_size 0
		.amdhsa_uses_dynamic_stack 0
		.amdhsa_enable_private_segment 0
		.amdhsa_system_sgpr_workgroup_id_x 1
		.amdhsa_system_sgpr_workgroup_id_y 0
		.amdhsa_system_sgpr_workgroup_id_z 0
		.amdhsa_system_sgpr_workgroup_info 0
		.amdhsa_system_vgpr_workitem_id 2
		.amdhsa_next_free_vgpr 256
		.amdhsa_next_free_sgpr 102
		.amdhsa_accum_offset 256
		.amdhsa_reserve_vcc 1
		.amdhsa_float_round_mode_32 0
		.amdhsa_float_round_mode_16_64 0
		.amdhsa_float_denorm_mode_32 3
		.amdhsa_float_denorm_mode_16_64 3
		.amdhsa_dx10_clamp 1
		.amdhsa_ieee_mode 1
		.amdhsa_fp16_overflow 0
		.amdhsa_tg_split 0
		.amdhsa_exception_fp_ieee_invalid_op 0
		.amdhsa_exception_fp_denorm_src 0
		.amdhsa_exception_fp_ieee_div_zero 0
		.amdhsa_exception_fp_ieee_overflow 0
		.amdhsa_exception_fp_ieee_underflow 0
		.amdhsa_exception_fp_ieee_inexact 0
		.amdhsa_exception_int_div_zero 0
	.end_amdhsa_kernel

amdhsa.kernels:
  - .agpr_count:     0
    .args:
      - .offset:         0
        .size:           200
        .value_kind:     by_value
      - .offset:         200
        .size:           4
        .value_kind:     hidden_block_count_x
      - .offset:         204
        .size:           4
        .value_kind:     hidden_block_count_y
      - .offset:         208
        .size:           4
        .value_kind:     hidden_block_count_z
      - .offset:         212
        .size:           2
        .value_kind:     hidden_group_size_x
      - .offset:         214
        .size:           2
        .value_kind:     hidden_group_size_y
      - .offset:         216
        .size:           2
        .value_kind:     hidden_group_size_z
      - .offset:         218
        .size:           2
        .value_kind:     hidden_remainder_x
      - .offset:         220
        .size:           2
        .value_kind:     hidden_remainder_y
      - .offset:         222
        .size:           2
        .value_kind:     hidden_remainder_z
      - .offset:         240
        .size:           8
        .value_kind:     hidden_global_offset_x
      - .offset:         248
        .size:           8
        .value_kind:     hidden_global_offset_y
      - .offset:         256
        .size:           8
        .value_kind:     hidden_global_offset_z
      - .offset:         264
        .size:           2
        .value_kind:     hidden_grid_dims
      - .offset:         288
        .size:           8
        .value_kind:     hidden_multigrid_sync_arg
    .group_segment_fixed_size: 131072
    .kernarg_segment_align: 8
    .kernarg_segment_size: 456
    .language:       OpenCL C
    .language_version:
      - 2
      - 0
    .max_flat_workgroup_size: 512
    .name:           _Z16trunk_megakernel6Params
    .private_segment_fixed_size: 0
    .sgpr_count:     108
    .sgpr_spill_count: 172
    .symbol:         _Z16trunk_megakernel6Params.kd
    .uniform_work_group_size: 1
    .uses_dynamic_stack: false
    .vgpr_count:     256
    .vgpr_spill_count: 0
    .wavefront_size: 64
